# prep: weight/input f32 loads without the nt (non-temporal) hint
# baseline (speedup 1.0000x reference)
; __device__ __forceinline__ unsigned cvt_pk_bf16(float lo, float hi) { unsigned r; asm volatile("v_cvt_pk_bf16_f32 %0, %1, %2" : "=v"(r) : "v"(lo), "v"(hi)); return r; }
; #define LAS __attribute__((address_space(3)))
; #define LDS_WAIT() asm volatile("s_waitcnt lgkmcnt(0)" ::: "memory")
; __device__ __forceinline__ void conv_item(const float* W, int ldw, int K, int c0, int k0, const float* gain, bf16_t* Wt, int n0, LAS float* scr, int lane) {
;     f32x4 v[16];
;     const int kr = lane >> 4, n4 = (lane & 15) * 4;
;     const float* src = W + (size_t)(k0 + kr) * ldw + c0 + n4;
; #pragma unroll
;     for (int i = 0; i < 16; ++i) v[i] = __builtin_nontemporal_load((const f32x4*)(src + (size_t)(4 * i) * ldw));
;     if (gain) {
; #pragma unroll
;         for (int i = 0; i < 16; ++i) v[i] = v[i] * gain[k0 + 4 * i + kr];
;     }
; #pragma unroll
;     for (int i = 0; i < 16; ++i) { const int k = 4 * i + kr; *(LAS f32x4*)(scr + k * 64 + (n4 ^ (((k >> 3) & 7) << 2))) = v[i]; }
;     LDS_WAIT(); asm volatile("" ::: "memory");
;     const int c = lane & 7;
; #pragma unroll
;     for (int j = 0; j < 8; ++j) { const int n = (lane >> 3) + 8 * j; const LAS float* s = scr + (8 * c) * 64 + (n ^ (c << 2));
;         u32x4 o; o.x = pg8::cvt_pk_bf16(s[0 * 64], s[1 * 64]); o.y = pg8::cvt_pk_bf16(s[2 * 64], s[3 * 64]); o.z = pg8::cvt_pk_bf16(s[4 * 64], s[5 * 64]); o.w = pg8::cvt_pk_bf16(s[6 * 64], s[7 * 64]);
;         *(u32x4*)(Wt + (size_t)(n0 + n) * K + k0 + 8 * c) = o; }
.LBB0_178:
	s_ashr_i32 s2, s15, 31
	s_lshr_b32 s2, s2, 28
	s_add_i32 s2, s15, s2
	s_ashr_i32 s3, s2, 4
	s_lshl_b32 s12, s3, 6
	v_or_b32_e32 v6, s12, v74
	s_lshl_b32 s2, s3, 10
	v_ashrrev_i32_e32 v7, 31, v6
	s_sub_i32 s2, s5, s2
	v_lshlrev_b64 v[6:7], 12, v[6:7]
	v_lshl_add_u64 v[6:7], s[0:1], 0, v[6:7]
	s_ashr_i32 s3, s2, 31
	v_lshl_add_u64 v[6:7], s[2:3], 2, v[6:7]
	v_lshlrev_b32_e32 v208, 2, v0
	v_lshl_add_u64 v[112:113], v[6:7], 0, v[208:209]
	v_add_co_u32_e32 v44, vcc, s17, v112
	global_load_dwordx4 v[6:9], v[112:113], off
	s_nop 0
	v_addc_co_u32_e32 v45, vcc, 0, v113, vcc
	v_add_co_u32_e32 v48, vcc, s18, v112
	global_load_dwordx4 v[44:47], v[44:45], off
	s_nop 0
	v_addc_co_u32_e32 v49, vcc, 0, v113, vcc
	v_add_co_u32_e32 v52, vcc, s19, v112
	global_load_dwordx4 v[48:51], v[48:49], off
	s_nop 0
	v_addc_co_u32_e32 v53, vcc, 0, v113, vcc
	v_add_co_u32_e32 v56, vcc, s20, v112
	global_load_dwordx4 v[52:55], v[52:53], off
	s_nop 0
	v_addc_co_u32_e32 v57, vcc, 0, v113, vcc
	v_add_co_u32_e32 v60, vcc, s21, v112
	global_load_dwordx4 v[56:59], v[56:57], off
	s_nop 0
	v_addc_co_u32_e32 v61, vcc, 0, v113, vcc
	v_add_co_u32_e32 v66, vcc, s26, v112
	global_load_dwordx4 v[60:63], v[60:61], off
	s_nop 0
	v_addc_co_u32_e32 v67, vcc, 0, v113, vcc
	v_add_co_u32_e32 v70, vcc, s27, v112
	global_load_dwordx4 v[66:69], v[66:67], off
	s_nop 0
	v_addc_co_u32_e32 v71, vcc, 0, v113, vcc
	v_add_co_u32_e32 v84, vcc, s28, v112
	global_load_dwordx4 v[70:73], v[70:71], off
	s_nop 0
	v_addc_co_u32_e32 v85, vcc, 0, v113, vcc
	v_add_co_u32_e32 v88, vcc, s29, v112
	global_load_dwordx4 v[84:87], v[84:85], off
	s_nop 0
	v_addc_co_u32_e32 v89, vcc, 0, v113, vcc
	v_add_co_u32_e32 v92, vcc, s30, v112
	global_load_dwordx4 v[88:91], v[88:89], off
	s_nop 0
	v_addc_co_u32_e32 v93, vcc, 0, v113, vcc
	v_add_co_u32_e32 v96, vcc, s31, v112
	global_load_dwordx4 v[92:95], v[92:93], off
	s_nop 0
	v_addc_co_u32_e32 v97, vcc, 0, v113, vcc
	v_add_co_u32_e32 v100, vcc, s36, v112
	global_load_dwordx4 v[96:99], v[96:97], off
	s_nop 0
	v_addc_co_u32_e32 v101, vcc, 0, v113, vcc
	v_add_co_u32_e32 v104, vcc, s37, v112
	global_load_dwordx4 v[100:103], v[100:101], off
	s_nop 0
	v_addc_co_u32_e32 v105, vcc, 0, v113, vcc
	v_add_co_u32_e32 v108, vcc, s38, v112
	global_load_dwordx4 v[104:107], v[104:105], off
	s_nop 0
	v_addc_co_u32_e32 v109, vcc, 0, v113, vcc
	v_add_co_u32_e32 v112, vcc, s39, v112
	global_load_dwordx4 v[108:111], v[108:109], off
	s_nop 0
	v_addc_co_u32_e32 v113, vcc, 0, v113, vcc
	global_load_dwordx4 v[112:115], v[112:113], off
	s_ashr_i32 s13, s12, 31
	s_add_i32 s15, s15, s16
	s_add_i32 s5, s5, s14
	s_cmpk_lt_i32 s15, 0x100
	s_waitcnt vmcnt(0)
	ds_write_b128 v27, v[6:9]
	s_waitcnt vmcnt(14)
	ds_write_b128 v27, v[44:47] offset:1024
	s_waitcnt vmcnt(13)
	ds_write_b128 v28, v[48:51] offset:2048
	s_waitcnt vmcnt(12)
	ds_write_b128 v28, v[52:55] offset:3072
	s_waitcnt vmcnt(11)
	ds_write_b128 v29, v[56:59] offset:4096
	s_waitcnt vmcnt(10)
	ds_write_b128 v29, v[60:63] offset:5120
	s_waitcnt vmcnt(9)
	ds_write_b128 v30, v[66:69] offset:6144
	s_waitcnt vmcnt(8)
	ds_write_b128 v30, v[70:73] offset:7168
	s_waitcnt vmcnt(7)
	ds_write_b128 v31, v[84:87] offset:8192
	s_waitcnt vmcnt(6)
	ds_write_b128 v31, v[88:91] offset:9216
	s_waitcnt vmcnt(5)
	ds_write_b128 v32, v[92:95] offset:10240
	s_waitcnt vmcnt(4)
	ds_write_b128 v32, v[96:99] offset:11264
	s_waitcnt vmcnt(3)
	ds_write_b128 v33, v[100:103] offset:12288
	s_waitcnt vmcnt(2)
	ds_write_b128 v33, v[104:107] offset:13312
	s_waitcnt vmcnt(1)
	ds_write_b128 v34, v[108:111] offset:14336
	s_waitcnt vmcnt(0)
	ds_write_b128 v34, v[112:115] offset:15360
	s_waitcnt lgkmcnt(0)
	ds_read2st64_b32 v[8:9], v35 offset1:1
	s_waitcnt lgkmcnt(0)
	v_cvt_pk_bf16_f32 v44, v8, v9
	ds_read2st64_b32 v[8:9], v35 offset0:2 offset1:3
	s_waitcnt lgkmcnt(0)
	v_cvt_pk_bf16_f32 v45, v8, v9
	ds_read2st64_b32 v[8:9], v35 offset0:4 offset1:5
	s_waitcnt lgkmcnt(0)
	v_cvt_pk_bf16_f32 v46, v8, v9
	ds_read2st64_b32 v[8:9], v35 offset0:6 offset1:7
	s_waitcnt lgkmcnt(0)
	v_cvt_pk_bf16_f32 v47, v8, v9
	v_add_u32_e32 v8, s2, v75
	v_ashrrev_i32_e32 v9, 31, v8
	v_lshl_add_u64 v[6:7], s[12:13], 1, v[4:5]
	v_lshlrev_b64 v[48:49], 11, v[8:9]
	v_lshl_add_u64 v[48:49], v[6:7], 0, v[48:49]
	global_store_dwordx4 v[48:49], v[44:47], off
	ds_read2st64_b32 v[44:45], v36 offset1:1
	s_waitcnt lgkmcnt(0)
; __device__ __forceinline__ unsigned cvt_pk_bf16(float lo, float hi) { unsigned r; asm volatile("v_cvt_pk_bf16_f32 %0, %1, %2" : "=v"(r) : "v"(lo), "v"(hi)); return r; }
; #define LAS __attribute__((address_space(3)))
; #define LDS_WAIT() asm volatile("s_waitcnt lgkmcnt(0)" ::: "memory")
; __device__ __forceinline__ void conv_item(const float* W, int ldw, int K, int c0, int k0, const float* gain, bf16_t* Wt, int n0, LAS float* scr, int lane) {
;     ...
;     const int c = lane & 7;
; #pragma unroll
;     for (int j = 0; j < 8; ++j) { const int n = (lane >> 3) + 8 * j; const LAS float* s = scr + (8 * c) * 64 + (n ^ (c << 2));
;         u32x4 o; o.x = pg8::cvt_pk_bf16(s[0 * 64], s[1 * 64]); o.y = pg8::cvt_pk_bf16(s[2 * 64], s[3 * 64]); o.z = pg8::cvt_pk_bf16(s[4 * 64], s[5 * 64]); o.w = pg8::cvt_pk_bf16(s[6 * 64], s[7 * 64]);
;         *(u32x4*)(Wt + (size_t)(n0 + n) * K + k0 + 8 * c) = o; }
;     LDS_WAIT(); asm volatile("" ::: "memory");
; }
	v_cvt_pk_bf16_f32 v44, v44, v45
	ds_read2st64_b32 v[46:47], v36 offset0:2 offset1:3
	s_waitcnt lgkmcnt(0)
	v_cvt_pk_bf16_f32 v45, v46, v47
	ds_read2st64_b32 v[46:47], v36 offset0:4 offset1:5
	s_waitcnt lgkmcnt(0)
	v_cvt_pk_bf16_f32 v46, v46, v47
	ds_read2st64_b32 v[48:49], v36 offset0:6 offset1:7
	s_waitcnt lgkmcnt(0)
	v_cvt_pk_bf16_f32 v47, v48, v49
	v_add_u32_e32 v48, 8, v8
	v_ashrrev_i32_e32 v49, 31, v48
	v_lshlrev_b64 v[48:49], 11, v[48:49]
	v_lshl_add_u64 v[48:49], v[6:7], 0, v[48:49]
	global_store_dwordx4 v[48:49], v[44:47], off
	ds_read2st64_b32 v[44:45], v37 offset1:1
	s_waitcnt lgkmcnt(0)
	v_cvt_pk_bf16_f32 v44, v44, v45
	ds_read2st64_b32 v[46:47], v37 offset0:2 offset1:3
	s_waitcnt lgkmcnt(0)
	v_cvt_pk_bf16_f32 v45, v46, v47
	ds_read2st64_b32 v[46:47], v37 offset0:4 offset1:5
	s_waitcnt lgkmcnt(0)
	v_cvt_pk_bf16_f32 v46, v46, v47
	ds_read2st64_b32 v[48:49], v37 offset0:6 offset1:7
	s_waitcnt lgkmcnt(0)
	v_cvt_pk_bf16_f32 v47, v48, v49
	v_add_u32_e32 v48, 16, v8
	v_ashrrev_i32_e32 v49, 31, v48
	v_lshlrev_b64 v[48:49], 11, v[48:49]
	v_lshl_add_u64 v[48:49], v[6:7], 0, v[48:49]
	global_store_dwordx4 v[48:49], v[44:47], off
	ds_read2st64_b32 v[44:45], v38 offset1:1
	s_waitcnt lgkmcnt(0)
	v_cvt_pk_bf16_f32 v44, v44, v45
	ds_read2st64_b32 v[46:47], v38 offset0:2 offset1:3
	s_waitcnt lgkmcnt(0)
	v_cvt_pk_bf16_f32 v45, v46, v47
	ds_read2st64_b32 v[46:47], v38 offset0:4 offset1:5
	s_waitcnt lgkmcnt(0)
	v_cvt_pk_bf16_f32 v46, v46, v47
	ds_read2st64_b32 v[48:49], v38 offset0:6 offset1:7
	s_waitcnt lgkmcnt(0)
	v_cvt_pk_bf16_f32 v47, v48, v49
	v_add_u32_e32 v48, 24, v8
	v_ashrrev_i32_e32 v49, 31, v48
	v_lshlrev_b64 v[48:49], 11, v[48:49]
	v_lshl_add_u64 v[48:49], v[6:7], 0, v[48:49]
	global_store_dwordx4 v[48:49], v[44:47], off
	ds_read2st64_b32 v[44:45], v39 offset1:1
	s_waitcnt lgkmcnt(0)
	v_cvt_pk_bf16_f32 v44, v44, v45
	ds_read2st64_b32 v[46:47], v39 offset0:2 offset1:3
	s_waitcnt lgkmcnt(0)
	v_cvt_pk_bf16_f32 v45, v46, v47
	ds_read2st64_b32 v[46:47], v39 offset0:4 offset1:5
	s_waitcnt lgkmcnt(0)
	v_cvt_pk_bf16_f32 v46, v46, v47
	ds_read2st64_b32 v[48:49], v39 offset0:6 offset1:7
	s_waitcnt lgkmcnt(0)
	v_cvt_pk_bf16_f32 v47, v48, v49
	v_add_u32_e32 v48, 32, v8
	v_ashrrev_i32_e32 v49, 31, v48
	v_lshlrev_b64 v[48:49], 11, v[48:49]
	v_lshl_add_u64 v[48:49], v[6:7], 0, v[48:49]
	global_store_dwordx4 v[48:49], v[44:47], off
	ds_read2st64_b32 v[44:45], v40 offset1:1
	s_waitcnt lgkmcnt(0)
	v_cvt_pk_bf16_f32 v44, v44, v45
	ds_read2st64_b32 v[46:47], v40 offset0:2 offset1:3
	s_waitcnt lgkmcnt(0)
	v_cvt_pk_bf16_f32 v45, v46, v47
	ds_read2st64_b32 v[46:47], v40 offset0:4 offset1:5
	s_waitcnt lgkmcnt(0)
	v_cvt_pk_bf16_f32 v46, v46, v47
	ds_read2st64_b32 v[48:49], v40 offset0:6 offset1:7
	s_waitcnt lgkmcnt(0)
	v_cvt_pk_bf16_f32 v47, v48, v49
	v_add_u32_e32 v48, 40, v8
	v_ashrrev_i32_e32 v49, 31, v48
	v_lshlrev_b64 v[48:49], 11, v[48:49]
	v_lshl_add_u64 v[48:49], v[6:7], 0, v[48:49]
	global_store_dwordx4 v[48:49], v[44:47], off
	ds_read2st64_b32 v[44:45], v41 offset1:1
	s_waitcnt lgkmcnt(0)
	v_cvt_pk_bf16_f32 v44, v44, v45
	ds_read2st64_b32 v[46:47], v41 offset0:2 offset1:3
	s_waitcnt lgkmcnt(0)
	v_cvt_pk_bf16_f32 v45, v46, v47
	ds_read2st64_b32 v[46:47], v41 offset0:4 offset1:5
	s_waitcnt lgkmcnt(0)
	v_cvt_pk_bf16_f32 v46, v46, v47
	ds_read2st64_b32 v[48:49], v41 offset0:6 offset1:7
	s_waitcnt lgkmcnt(0)
	v_cvt_pk_bf16_f32 v47, v48, v49
	v_add_u32_e32 v48, 48, v8
	v_ashrrev_i32_e32 v49, 31, v48
	v_lshlrev_b64 v[48:49], 11, v[48:49]
	v_lshl_add_u64 v[48:49], v[6:7], 0, v[48:49]
	v_add_u32_e32 v8, 56, v8
	global_store_dwordx4 v[48:49], v[44:47], off
	ds_read2st64_b32 v[44:45], v42 offset1:1
	v_ashrrev_i32_e32 v9, 31, v8
	s_waitcnt lgkmcnt(0)
	v_cvt_pk_bf16_f32 v44, v44, v45
	ds_read2st64_b32 v[46:47], v42 offset0:2 offset1:3
	v_lshlrev_b64 v[8:9], 11, v[8:9]
	s_waitcnt lgkmcnt(0)
	v_cvt_pk_bf16_f32 v45, v46, v47
	ds_read2st64_b32 v[46:47], v42 offset0:4 offset1:5
	v_lshl_add_u64 v[6:7], v[6:7], 0, v[8:9]
	s_waitcnt lgkmcnt(0)
	v_cvt_pk_bf16_f32 v46, v46, v47
	ds_read2st64_b32 v[48:49], v42 offset0:6 offset1:7
	s_waitcnt lgkmcnt(0)
	v_cvt_pk_bf16_f32 v47, v48, v49
	global_store_dwordx4 v[6:7], v[44:47], off
	s_waitcnt lgkmcnt(0)
	s_cbranch_scc1 .LBB0_178
	s_mov_b32 s66, 0x1c000
	s_mov_b32 s65, 0xc000
	v_mov_b64_e32 v[66:67], v[0:1]

; #define LAS __attribute__((address_space(3)))
; __device__ __forceinline__ void conv_item(const float* W, int ldw, int K, int c0, int k0, const float* gain, bf16_t* Wt, int n0, LAS float* scr, int lane) {
;     f32x4 v[16];
;     const int kr = lane >> 4, n4 = (lane & 15) * 4;
;     const float* src = W + (size_t)(k0 + kr) * ldw + c0 + n4;
; #pragma unroll
;     for (int i = 0; i < 16; ++i) v[i] = __builtin_nontemporal_load((const f32x4*)(src + (size_t)(4 * i) * ldw));
;     if (gain) {
; #pragma unroll
;         for (int i = 0; i < 16; ++i) v[i] = v[i] * gain[k0 + 4 * i + kr];
; __device__ __forceinline__ int map_col(int kind, int arg, int n0) {
;     if (kind == MAP_GLU) { const int pn = n0 >> 8, w = n0 & 255; return (w >> 7) * 1024 + pn * 128 + (w & 127); }
;     if (kind == MAP_QKV) { return ((n0 >> 10) * 3 + arg) * 1024 + (n0 & 1023); }
;     return n0;
; }
; __device__ __forceinline__ void conv_matrix(const float* W, int ldw, int K, int N, int kind, int arg, const float* gain, bf16_t* Wt, LAS float* scr, int lane, int gw, int NGW, int& rot) {
;     const int nblk = N / 64, nitems = (K / 64) * nblk;
;     for (int it = (gw + NGW - rot) % NGW; it < nitems; it += NGW) { const int kb = it / nblk, nb = it % nblk; conv_item(W, ldw, K, map_col(kind, arg, nb * 64), kb * 64, gain, Wt, nb * 64, scr, lane); }
.LBB0_185:
	s_mul_hi_i32 s16, s5, 0x2aaaaaab
	s_lshr_b32 s17, s16, 31
	s_ashr_i32 s16, s16, 3
	s_add_i32 s16, s16, s17
	s_mul_i32 s17, s16, 0xffffffd0
	s_add_i32 s17, s5, s17
	s_lshr_b32 s17, s17, 4
	s_mul_i32 s21, s16, 0xfffff400
	s_mul_i32 s17, s17, 3
	s_add_i32 s21, s18, s21
	v_add_u32_e32 v0, s17, v99
	v_lshlrev_b32_e32 v0, 10, v0
	s_and_b32 s17, s21, 0x3c0
	s_lshl_b32 s16, s16, 6
	v_or_b32_e32 v0, s17, v0
	v_or_b32_e32 v72, s16, v74
	v_mov_b64_e32 v[2:3], s[2:3]
	s_mov_b32 s17, 0x9000
	v_mad_i64_i32 v[2:3], s[26:27], v72, s17, v[2:3]
	v_ashrrev_i32_e32 v1, 31, v0
	v_lshl_add_u64 v[0:1], v[0:1], 2, v[2:3]
	v_lshl_add_u64 v[56:57], v[66:67], 2, v[0:1]
	s_mov_b32 s17, 0x24000
	v_add_co_u32_e32 v4, vcc, s17, v56
	s_mov_b32 s17, 0x48000
	s_nop 0
	v_addc_co_u32_e32 v5, vcc, 0, v57, vcc
	v_add_co_u32_e32 v8, vcc, s17, v56
	s_mov_b32 s17, 0x6c000
	s_nop 0
	v_addc_co_u32_e32 v9, vcc, 0, v57, vcc
	v_add_co_u32_e32 v12, vcc, s17, v56
	s_mov_b32 s17, 0x90000
	s_nop 0
	v_addc_co_u32_e32 v13, vcc, 0, v57, vcc
	v_add_co_u32_e32 v16, vcc, s17, v56
	s_mov_b32 s17, 0xb4000
	s_nop 0
	v_addc_co_u32_e32 v17, vcc, 0, v57, vcc
	v_add_co_u32_e32 v20, vcc, s17, v56
	s_mov_b32 s17, 0xd8000
	s_nop 0
	v_addc_co_u32_e32 v21, vcc, 0, v57, vcc
	v_add_co_u32_e32 v24, vcc, s17, v56
	s_mov_b32 s17, 0xfc000
	s_nop 0
	v_addc_co_u32_e32 v25, vcc, 0, v57, vcc
	v_add_co_u32_e32 v28, vcc, s17, v56
	s_mov_b32 s17, 0x120000
	s_nop 0
	v_addc_co_u32_e32 v29, vcc, 0, v57, vcc
	v_add_co_u32_e32 v32, vcc, s17, v56
	s_mov_b32 s17, 0x144000
	s_nop 0
	v_addc_co_u32_e32 v33, vcc, 0, v57, vcc
	v_add_co_u32_e32 v36, vcc, s17, v56
	s_mov_b32 s17, 0x168000
	s_nop 0
	v_addc_co_u32_e32 v37, vcc, 0, v57, vcc
	v_add_co_u32_e32 v40, vcc, s17, v56
	s_mov_b32 s17, 0x18c000
	s_nop 0
	v_addc_co_u32_e32 v41, vcc, 0, v57, vcc
	v_add_co_u32_e32 v44, vcc, s17, v56
	s_mov_b32 s17, 0x1b0000
	s_nop 0
	v_addc_co_u32_e32 v45, vcc, 0, v57, vcc
	v_add_co_u32_e32 v48, vcc, s17, v56
	global_load_dwordx4 v[0:3], v[56:57], off
	s_nop 0
	global_load_dwordx4 v[4:7], v[4:5], off
	v_addc_co_u32_e32 v49, vcc, 0, v57, vcc
	v_add_co_u32_e32 v52, vcc, 0x1d4000, v56
	global_load_dwordx4 v[8:11], v[8:9], off
	s_nop 0
	global_load_dwordx4 v[12:15], v[12:13], off
	v_addc_co_u32_e32 v53, vcc, 0, v57, vcc
	v_add_co_u32_e32 v58, vcc, 0x1f8000, v56
	global_load_dwordx4 v[16:19], v[16:17], off
	s_nop 0
	global_load_dwordx4 v[20:23], v[20:21], off
	v_addc_co_u32_e32 v59, vcc, 0, v57, vcc
	v_add_co_u32_e32 v60, vcc, 0x21c000, v56
	global_load_dwordx4 v[24:27], v[24:25], off
	s_nop 0
	global_load_dwordx4 v[28:31], v[28:29], off
	v_addc_co_u32_e32 v61, vcc, 0, v57, vcc
	global_load_dwordx4 v[32:35], v[32:33], off
	s_nop 0
	global_load_dwordx4 v[36:39], v[36:37], off
	s_nop 0
	global_load_dwordx4 v[40:43], v[40:41], off
	s_nop 0
	global_load_dwordx4 v[44:47], v[44:45], off
	s_nop 0
	global_load_dwordx4 v[48:51], v[48:49], off
	s_nop 0
	global_load_dwordx4 v[52:55], v[52:53], off
	s_nop 0
	global_load_dwordx4 v[56:59], v[58:59], off
	s_nop 0
	global_load_dwordx4 v[60:63], v[60:61], off
	s_andn2_b64 vcc, exec, s[14:15]
	s_cbranch_vccnz .LBB0_184
	v_ashrrev_i32_e32 v73, 31, v72
	v_lshl_add_u64 v[72:73], v[72:73], 2, s[12:13]
	global_load_dword v100, v[72:73], off
	global_load_dword v102, v[72:73], off offset:16
	global_load_dword v104, v[72:73], off offset:32
	global_load_dword v106, v[72:73], off offset:48
	global_load_dword v108, v[72:73], off offset:64
	global_load_dword v110, v[72:73], off offset:80
	global_load_dword v112, v[72:73], off offset:96
	global_load_dword v114, v[72:73], off offset:112
	global_load_dword v116, v[72:73], off offset:128
	global_load_dword v118, v[72:73], off offset:144
	global_load_dword v120, v[72:73], off offset:160
	global_load_dword v122, v[72:73], off offset:176
	global_load_dword v124, v[72:73], off offset:192
	global_load_dword v126, v[72:73], off offset:208
	global_load_dword v128, v[72:73], off offset:224
	s_nop 0
	global_load_dword v72, v[72:73], off offset:240
	s_waitcnt vmcnt(0)
	v_pk_mul_f32 v[2:3], v[2:3], v[100:101] op_sel_hi:[1,0]
	v_pk_mul_f32 v[0:1], v[0:1], v[100:101] op_sel_hi:[1,0]
	s_waitcnt vmcnt(14)
	v_pk_mul_f32 v[6:7], v[6:7], v[102:103] op_sel_hi:[1,0]
	v_pk_mul_f32 v[4:5], v[4:5], v[102:103] op_sel_hi:[1,0]
	s_waitcnt vmcnt(13)
	v_pk_mul_f32 v[10:11], v[10:11], v[104:105] op_sel_hi:[1,0]
	v_pk_mul_f32 v[8:9], v[8:9], v[104:105] op_sel_hi:[1,0]
	s_waitcnt vmcnt(12)
	v_pk_mul_f32 v[14:15], v[14:15], v[106:107] op_sel_hi:[1,0]
	v_pk_mul_f32 v[12:13], v[12:13], v[106:107] op_sel_hi:[1,0]
	s_waitcnt vmcnt(11)
	v_pk_mul_f32 v[18:19], v[18:19], v[108:109] op_sel_hi:[1,0]
	v_pk_mul_f32 v[16:17], v[16:17], v[108:109] op_sel_hi:[1,0]
	s_waitcnt vmcnt(10)
	v_pk_mul_f32 v[22:23], v[22:23], v[110:111] op_sel_hi:[1,0]
	v_pk_mul_f32 v[20:21], v[20:21], v[110:111] op_sel_hi:[1,0]
	s_waitcnt vmcnt(9)
	v_pk_mul_f32 v[26:27], v[26:27], v[112:113] op_sel_hi:[1,0]
	v_pk_mul_f32 v[24:25], v[24:25], v[112:113] op_sel_hi:[1,0]
	s_waitcnt vmcnt(8)
	v_pk_mul_f32 v[30:31], v[30:31], v[114:115] op_sel_hi:[1,0]
	v_pk_mul_f32 v[28:29], v[28:29], v[114:115] op_sel_hi:[1,0]
	s_waitcnt vmcnt(7)
	v_pk_mul_f32 v[34:35], v[34:35], v[116:117] op_sel_hi:[1,0]
	v_pk_mul_f32 v[32:33], v[32:33], v[116:117] op_sel_hi:[1,0]
	s_waitcnt vmcnt(6)
	v_pk_mul_f32 v[38:39], v[38:39], v[118:119] op_sel_hi:[1,0]
	v_pk_mul_f32 v[36:37], v[36:37], v[118:119] op_sel_hi:[1,0]
	s_waitcnt vmcnt(5)
	v_pk_mul_f32 v[42:43], v[42:43], v[120:121] op_sel_hi:[1,0]
	v_pk_mul_f32 v[40:41], v[40:41], v[120:121] op_sel_hi:[1,0]
	s_waitcnt vmcnt(4)
	v_pk_mul_f32 v[46:47], v[46:47], v[122:123] op_sel_hi:[1,0]
	v_pk_mul_f32 v[44:45], v[44:45], v[122:123] op_sel_hi:[1,0]
	s_waitcnt vmcnt(3)
	v_pk_mul_f32 v[50:51], v[50:51], v[124:125] op_sel_hi:[1,0]
	v_pk_mul_f32 v[48:49], v[48:49], v[124:125] op_sel_hi:[1,0]
	s_waitcnt vmcnt(2)
	v_pk_mul_f32 v[54:55], v[54:55], v[126:127] op_sel_hi:[1,0]
	v_pk_mul_f32 v[52:53], v[52:53], v[126:127] op_sel_hi:[1,0]
	s_waitcnt vmcnt(1)
	v_pk_mul_f32 v[58:59], v[58:59], v[128:129] op_sel_hi:[1,0]
	v_pk_mul_f32 v[56:57], v[56:57], v[128:129] op_sel_hi:[1,0]
	s_waitcnt vmcnt(0)
	v_pk_mul_f32 v[62:63], v[62:63], v[72:73] op_sel_hi:[1,0]
	v_pk_mul_f32 v[60:61], v[60:61], v[72:73] op_sel_hi:[1,0]
	s_branch .LBB0_184

; #define LAS __attribute__((address_space(3)))
; __device__ __forceinline__ void conv_item(const float* W, int ldw, int K, int c0, int k0, const float* gain, bf16_t* Wt, int n0, LAS float* scr, int lane) {
;     f32x4 v[16];
;     const int kr = lane >> 4, n4 = (lane & 15) * 4;
;     const float* src = W + (size_t)(k0 + kr) * ldw + c0 + n4;
; #pragma unroll
;     for (int i = 0; i < 16; ++i) v[i] = __builtin_nontemporal_load((const f32x4*)(src + (size_t)(4 * i) * ldw));
;     if (gain) {
; #pragma unroll
;         for (int i = 0; i < 16; ++i) v[i] = v[i] * gain[k0 + 4 * i + kr];
;     }
; #pragma unroll
;     for (int i = 0; i < 16; ++i) { const int k = 4 * i + kr; *(LAS f32x4*)(scr + k * 64 + (n4 ^ (((k >> 3) & 7) << 2))) = v[i]; }
; __device__ __forceinline__ int map_col(int kind, int arg, int n0) {
;     if (kind == MAP_GLU) { const int pn = n0 >> 8, w = n0 & 255; return (w >> 7) * 1024 + pn * 128 + (w & 127); }
;     if (kind == MAP_QKV) { return ((n0 >> 10) * 3 + arg) * 1024 + (n0 & 1023); }
;     return n0;
; }
; __device__ __forceinline__ void conv_matrix(const float* W, int ldw, int K, int N, int kind, int arg, const float* gain, bf16_t* Wt, LAS float* scr, int lane, int gw, int NGW, int& rot) {
;     const int nblk = N / 64, nitems = (K / 64) * nblk;
;     for (int it = (gw + NGW - rot) % NGW; it < nitems; it += NGW) { const int kb = it / nblk, nb = it % nblk; conv_item(W, ldw, K, map_col(kind, arg, nb * 64), kb * 64, gain, Wt, nb * 64, scr, lane); }
.LBB0_259:
	s_ashr_i32 s2, s17, 31
	s_lshr_b32 s2, s2, 27
	s_add_i32 s2, s17, s2
	s_ashr_i32 s2, s2, 5
	s_lshl_b32 s3, s2, 11
	s_lshl_b32 s19, s2, 10
	s_lshl_b32 s2, s2, 6
	s_sub_i32 s18, s5, s3
	s_sub_i32 s3, s13, s3
	s_sub_i32 s19, s15, s19
	v_or_b32_e32 v0, s2, v34
	s_and_b32 s3, s3, 0x400
	s_and_b32 s19, s19, 0xffffff80
	s_and_b32 s20, s18, 64
	v_ashrrev_i32_e32 v1, 31, v0
	s_add_i32 s3, s3, s19
	v_lshlrev_b64 v[0:1], 13, v[0:1]
	s_or_b32 s20, s3, s20
	v_lshl_add_u64 v[0:1], s[0:1], 0, v[0:1]
	s_ashr_i32 s21, s20, 31
	v_lshl_add_u64 v[0:1], s[20:21], 2, v[0:1]
	v_lshl_add_u64 v[4:5], v[0:1], 0, v[208:209]
	v_add_co_u32_e32 v6, vcc, s27, v4
	global_load_dwordx4 v[0:3], v[4:5], off
	s_nop 0
	v_addc_co_u32_e32 v7, vcc, 0, v5, vcc
	v_add_co_u32_e32 v8, vcc, s29, v4
	s_mov_b32 s3, 0x68000
	s_nop 0
	v_addc_co_u32_e32 v9, vcc, 0, v5, vcc
	v_add_co_u32_e32 v12, vcc, s30, v4
	s_add_i32 s17, s17, s26
	s_nop 0
	v_addc_co_u32_e32 v13, vcc, 0, v5, vcc
	v_add_co_u32_e32 v14, vcc, s31, v4
	s_add_i32 s5, s5, s12
	s_nop 0
	v_addc_co_u32_e32 v15, vcc, 0, v5, vcc
	v_add_co_u32_e32 v20, vcc, s36, v4
	s_add_i32 s13, s13, s14
	s_nop 0
	v_addc_co_u32_e32 v21, vcc, 0, v5, vcc
	v_add_co_u32_e32 v22, vcc, s37, v4
	s_add_i32 s15, s15, s16
	s_nop 0
	v_addc_co_u32_e32 v23, vcc, 0, v5, vcc
	v_add_co_u32_e32 v30, vcc, s38, v4
	s_mov_b32 s20, s28
	s_nop 0
	v_addc_co_u32_e32 v31, vcc, 0, v5, vcc
	v_add_co_u32_e32 v32, vcc, s40, v4
	s_nop 1
	v_addc_co_u32_e32 v33, vcc, 0, v5, vcc
	v_add_co_u32_e32 v72, vcc, s39, v4
	s_nop 1
	v_addc_co_u32_e32 v73, vcc, 0, v5, vcc
	v_add_co_u32_e32 v74, vcc, s41, v4
	s_nop 1
	v_addc_co_u32_e32 v75, vcc, 0, v5, vcc
	v_add_co_u32_e32 v76, vcc, s42, v4
	s_nop 1
	v_addc_co_u32_e32 v77, vcc, 0, v5, vcc
	v_add_co_u32_e32 v78, vcc, s43, v4
	s_nop 1
	v_addc_co_u32_e32 v79, vcc, 0, v5, vcc
	v_add_co_u32_e32 v80, vcc, s3, v4
	s_mov_b32 s3, 0x78000
	s_nop 0
	v_addc_co_u32_e32 v81, vcc, 0, v5, vcc
	v_add_co_u32_e32 v82, vcc, s44, v4
	s_nop 1
	v_addc_co_u32_e32 v83, vcc, 0, v5, vcc
	v_add_co_u32_e32 v84, vcc, s3, v4
	s_ashr_i32 s3, s2, 31
	s_nop 0
	v_addc_co_u32_e32 v85, vcc, 0, v5, vcc
	global_load_dwordx4 v[4:7], v[6:7], off
	s_nop 0
	global_load_dwordx4 v[8:11], v[8:9], off
	s_nop 0
	global_load_dwordx4 v[16:19], v[12:13], off
	global_load_dwordx4 v[24:27], v[14:15], off
	global_load_dwordx4 v[52:55], v[20:21], off
	global_load_dwordx4 v[56:59], v[22:23], off
	s_cmpk_gt_i32 s17, 0x1ff
	s_waitcnt vmcnt(0)
	ds_write_b128 v35, v[0:3]
	global_load_dwordx4 v[60:63], v[30:31], off
	global_load_dwordx4 v[68:71], v[32:33], off
	v_add_u32_e32 v32, s18, v43
	v_ashrrev_i32_e32 v33, 31, v32
	v_lshl_add_u64 v[30:31], s[2:3], 1, v[28:29]
	s_waitcnt vmcnt(7)
	ds_write_b128 v35, v[4:7] offset:1024
	global_load_dwordx4 v[0:3], v[72:73], off
	global_load_dwordx4 v[4:7], v[74:75], off
	s_waitcnt vmcnt(8)
	ds_write_b128 v36, v[8:11] offset:2048
	global_load_dwordx4 v[8:11], v[76:77], off
	global_load_dwordx4 v[12:15], v[78:79], off
	s_waitcnt vmcnt(9)
	ds_write_b128 v36, v[16:19] offset:3072
	global_load_dwordx4 v[16:19], v[80:81], off
	global_load_dwordx4 v[20:23], v[82:83], off
	s_waitcnt vmcnt(10)
	ds_write_b128 v37, v[24:27] offset:4096
	global_load_dwordx4 v[24:27], v[84:85], off
	s_waitcnt vmcnt(10)
	ds_write_b128 v37, v[52:55] offset:5120
	s_waitcnt vmcnt(9)
	ds_write_b128 v38, v[56:59] offset:6144
	v_add_u32_e32 v52, 8, v32
	v_ashrrev_i32_e32 v53, 31, v52
	s_waitcnt vmcnt(8)
	ds_write_b128 v38, v[60:63] offset:7168
	s_waitcnt vmcnt(7)
	ds_write_b128 v39, v[68:71] offset:8192
	v_lshlrev_b64 v[68:69], 11, v[32:33]
	v_lshl_add_u64 v[68:69], v[30:31], 0, v[68:69]
	v_lshlrev_b64 v[52:53], 11, v[52:53]
	v_add_u32_e32 v54, 16, v32
	v_lshl_add_u64 v[52:53], v[30:31], 0, v[52:53]
	v_ashrrev_i32_e32 v55, 31, v54
	v_lshlrev_b64 v[54:55], 11, v[54:55]
	v_add_u32_e32 v56, 24, v32
	v_lshl_add_u64 v[54:55], v[30:31], 0, v[54:55]
	v_ashrrev_i32_e32 v57, 31, v56
	v_lshlrev_b64 v[56:57], 11, v[56:57]
	v_add_u32_e32 v58, 32, v32
	v_lshl_add_u64 v[56:57], v[30:31], 0, v[56:57]
	s_waitcnt vmcnt(6)
	ds_write_b128 v39, v[0:3] offset:9216
	s_waitcnt vmcnt(5)
	ds_write_b128 v40, v[4:7] offset:10240
	s_waitcnt vmcnt(4)
	ds_write_b128 v40, v[8:11] offset:11264
	s_waitcnt vmcnt(3)
	ds_write_b128 v41, v[12:15] offset:12288
	s_waitcnt vmcnt(2)
; __device__ __forceinline__ unsigned cvt_pk_bf16(float lo, float hi) { unsigned r; asm volatile("v_cvt_pk_bf16_f32 %0, %1, %2" : "=v"(r) : "v"(lo), "v"(hi)); return r; }
; #define LAS __attribute__((address_space(3)))
; #define LDS_WAIT() asm volatile("s_waitcnt lgkmcnt(0)" ::: "memory")
; __device__ __forceinline__ void conv_item(const float* W, int ldw, int K, int c0, int k0, const float* gain, bf16_t* Wt, int n0, LAS float* scr, int lane) {
;     ...
;     for (int i = 0; i < 16; ++i) { const int k = 4 * i + kr; *(LAS f32x4*)(scr + k * 64 + (n4 ^ (((k >> 3) & 7) << 2))) = v[i]; }
;     LDS_WAIT(); asm volatile("" ::: "memory");
;     const int c = lane & 7;
; #pragma unroll
;     for (int j = 0; j < 8; ++j) { const int n = (lane >> 3) + 8 * j; const LAS float* s = scr + (8 * c) * 64 + (n ^ (c << 2));
;         u32x4 o; o.x = pg8::cvt_pk_bf16(s[0 * 64], s[1 * 64]); o.y = pg8::cvt_pk_bf16(s[2 * 64], s[3 * 64]); o.z = pg8::cvt_pk_bf16(s[4 * 64], s[5 * 64]); o.w = pg8::cvt_pk_bf16(s[6 * 64], s[7 * 64]);
;         *(u32x4*)(Wt + (size_t)(n0 + n) * K + k0 + 8 * c) = o; }
;     LDS_WAIT(); asm volatile("" ::: "memory");
	ds_write_b128 v41, v[16:19] offset:13312
	s_waitcnt vmcnt(1)
	ds_write_b128 v42, v[20:23] offset:14336
	s_waitcnt vmcnt(0)
	ds_write_b128 v42, v[24:27] offset:15360
	s_waitcnt lgkmcnt(0)
	ds_read2st64_b32 v[0:1], v44 offset1:1
	s_waitcnt lgkmcnt(0)
	v_cvt_pk_bf16_f32 v0, v0, v1
	ds_read2st64_b32 v[2:3], v44 offset0:2 offset1:3
	s_waitcnt lgkmcnt(0)
	v_cvt_pk_bf16_f32 v1, v2, v3
	ds_read2st64_b32 v[2:3], v44 offset0:4 offset1:5
	s_waitcnt lgkmcnt(0)
	v_cvt_pk_bf16_f32 v2, v2, v3
	ds_read2st64_b32 v[4:5], v44 offset0:6 offset1:7
	s_waitcnt lgkmcnt(0)
	v_cvt_pk_bf16_f32 v3, v4, v5
	ds_read2st64_b32 v[4:5], v45 offset1:1
	global_store_dwordx4 v[68:69], v[0:3], off
	v_ashrrev_i32_e32 v59, 31, v58
	v_lshlrev_b64 v[58:59], 11, v[58:59]
	s_waitcnt lgkmcnt(0)
	v_cvt_pk_bf16_f32 v0, v4, v5
	ds_read2st64_b32 v[2:3], v45 offset0:2 offset1:3
	s_waitcnt lgkmcnt(0)
	v_cvt_pk_bf16_f32 v1, v2, v3
	ds_read2st64_b32 v[2:3], v45 offset0:4 offset1:5
	s_waitcnt lgkmcnt(0)
	v_cvt_pk_bf16_f32 v2, v2, v3
	ds_read2st64_b32 v[4:5], v45 offset0:6 offset1:7
	s_waitcnt lgkmcnt(0)
	v_cvt_pk_bf16_f32 v3, v4, v5
	ds_read2st64_b32 v[4:5], v46 offset1:1
	global_store_dwordx4 v[52:53], v[0:3], off
	v_add_u32_e32 v60, 40, v32
	v_lshl_add_u64 v[58:59], v[30:31], 0, v[58:59]
	s_waitcnt lgkmcnt(0)
	v_cvt_pk_bf16_f32 v0, v4, v5
	ds_read2st64_b32 v[2:3], v46 offset0:2 offset1:3
	s_waitcnt lgkmcnt(0)
	v_cvt_pk_bf16_f32 v1, v2, v3
	ds_read2st64_b32 v[2:3], v46 offset0:4 offset1:5
	s_waitcnt lgkmcnt(0)
	v_cvt_pk_bf16_f32 v2, v2, v3
	ds_read2st64_b32 v[4:5], v46 offset0:6 offset1:7
	s_waitcnt lgkmcnt(0)
	v_cvt_pk_bf16_f32 v3, v4, v5
	ds_read2st64_b32 v[4:5], v47 offset1:1
	global_store_dwordx4 v[54:55], v[0:3], off
	v_ashrrev_i32_e32 v61, 31, v60
	v_lshlrev_b64 v[60:61], 11, v[60:61]
	s_waitcnt lgkmcnt(0)
	v_cvt_pk_bf16_f32 v0, v4, v5
	ds_read2st64_b32 v[2:3], v47 offset0:2 offset1:3
	s_waitcnt lgkmcnt(0)
	v_cvt_pk_bf16_f32 v1, v2, v3
	ds_read2st64_b32 v[2:3], v47 offset0:4 offset1:5
	s_waitcnt lgkmcnt(0)
	v_cvt_pk_bf16_f32 v2, v2, v3
	ds_read2st64_b32 v[4:5], v47 offset0:6 offset1:7
	s_waitcnt lgkmcnt(0)
	v_cvt_pk_bf16_f32 v3, v4, v5
	ds_read2st64_b32 v[4:5], v48 offset1:1
	global_store_dwordx4 v[56:57], v[0:3], off
	v_add_u32_e32 v62, 48, v32
	v_lshl_add_u64 v[60:61], v[30:31], 0, v[60:61]
	s_waitcnt lgkmcnt(0)
	v_cvt_pk_bf16_f32 v0, v4, v5
	ds_read2st64_b32 v[2:3], v48 offset0:2 offset1:3
	s_waitcnt lgkmcnt(0)
	v_cvt_pk_bf16_f32 v1, v2, v3
	ds_read2st64_b32 v[2:3], v48 offset0:4 offset1:5
	s_waitcnt lgkmcnt(0)
	v_cvt_pk_bf16_f32 v2, v2, v3
	ds_read2st64_b32 v[4:5], v48 offset0:6 offset1:7
	s_waitcnt lgkmcnt(0)
	v_cvt_pk_bf16_f32 v3, v4, v5
	ds_read2st64_b32 v[4:5], v49 offset1:1
	global_store_dwordx4 v[58:59], v[0:3], off
	v_ashrrev_i32_e32 v63, 31, v62
	v_lshlrev_b64 v[62:63], 11, v[62:63]
	s_waitcnt lgkmcnt(0)
	v_cvt_pk_bf16_f32 v0, v4, v5
	ds_read2st64_b32 v[2:3], v49 offset0:2 offset1:3
	s_waitcnt lgkmcnt(0)
	v_cvt_pk_bf16_f32 v1, v2, v3
	ds_read2st64_b32 v[2:3], v49 offset0:4 offset1:5
	s_waitcnt lgkmcnt(0)
	v_cvt_pk_bf16_f32 v2, v2, v3
	ds_read2st64_b32 v[4:5], v49 offset0:6 offset1:7
	s_waitcnt lgkmcnt(0)
	v_cvt_pk_bf16_f32 v3, v4, v5
	ds_read2st64_b32 v[4:5], v50 offset1:1
	global_store_dwordx4 v[60:61], v[0:3], off
	v_add_u32_e32 v6, 56, v32
	v_lshl_add_u64 v[62:63], v[30:31], 0, v[62:63]
	s_waitcnt lgkmcnt(0)
	v_cvt_pk_bf16_f32 v0, v4, v5
	ds_read2st64_b32 v[2:3], v50 offset0:2 offset1:3
	s_waitcnt lgkmcnt(0)
	v_cvt_pk_bf16_f32 v1, v2, v3
	ds_read2st64_b32 v[2:3], v50 offset0:4 offset1:5
	s_waitcnt lgkmcnt(0)
	v_cvt_pk_bf16_f32 v2, v2, v3
	ds_read2st64_b32 v[4:5], v50 offset0:6 offset1:7
	s_waitcnt lgkmcnt(0)
	v_cvt_pk_bf16_f32 v3, v4, v5
	v_ashrrev_i32_e32 v7, 31, v6
	ds_read2st64_b32 v[4:5], v51 offset1:1
	global_store_dwordx4 v[62:63], v[0:3], off
	v_lshlrev_b64 v[6:7], 11, v[6:7]
	v_lshl_add_u64 v[6:7], v[30:31], 0, v[6:7]
	s_waitcnt lgkmcnt(0)
	v_cvt_pk_bf16_f32 v0, v4, v5
	ds_read2st64_b32 v[2:3], v51 offset0:2 offset1:3
	s_waitcnt lgkmcnt(0)
	v_cvt_pk_bf16_f32 v1, v2, v3
	ds_read2st64_b32 v[2:3], v51 offset0:4 offset1:5
	s_waitcnt lgkmcnt(0)
	v_cvt_pk_bf16_f32 v2, v2, v3
	ds_read2st64_b32 v[4:5], v51 offset0:6 offset1:7
	s_waitcnt lgkmcnt(0)
	v_cvt_pk_bf16_f32 v3, v4, v5
	global_store_dwordx4 v[6:7], v[0:3], off
	s_waitcnt lgkmcnt(0)
	s_cbranch_scc0 .LBB0_259

; __device__ __forceinline__ unsigned cvt_pk_bf16(float lo, float hi) { unsigned r; asm volatile("v_cvt_pk_bf16_f32 %0, %1, %2" : "=v"(r) : "v"(lo), "v"(hi)); return r; }
; #define LAS __attribute__((address_space(3)))
; template <bool F32SRC> __device__ __forceinline__ void unorm_chunk(LAS unsigned char* lds, const float* xsrc, bf16_t* hbio, bf16_t* Ug, int chunk, const int tid) {
;     const int lane = tid & 63, wid = __builtin_amdgcn_readfirstlane(tid >> 6);
;     LAS unsigned char* T = lds;
; #pragma unroll
;     for (int rr = 0; rr < 2; ++rr) { const int s = 2 * wid + rr; const size_t row = (size_t)chunk * 16 + s;
;         if (F32SRC) { const f32x4* xr = (const f32x4*)(xsrc + row * DM) + lane; f32x4 v[4]; float ss = 0.f;
; #pragma unroll
;             for (int j = 0; j < 4; ++j) { v[j] = __builtin_nontemporal_load(xr + 64 * j); ss += (v[j].x * v[j].x + v[j].y * v[j].y) + (v[j].z * v[j].z + v[j].w * v[j].w); }
;             const float rstd = rsqrtf(wsum_l(ss, lane) * (1.0f / DM) + EPS);
;             u32x2* o = (u32x2*)(hbio + row * DM) + lane;
; #pragma unroll
;             for (int j = 0; j < 4; ++j) { u32x2 w; w.x = pg8::cvt_pk_bf16(v[j].x, v[j].y); w.y = pg8::cvt_pk_bf16(v[j].z, v[j].w); o[64 * j] = w;
;                 u32x2 q; q.x = pg8::cvt_pk_bf16(v[j].x * rstd, v[j].y * rstd); q.y = pg8::cvt_pk_bf16(v[j].z * rstd, v[j].w * rstd); *(LAS u32x2*)(T + s * 2080 + (64 * j + lane) * 8) = q; }
.LBB0_312:
	ds_read_b64 v[6:7], v236
	ds_read_b64 v[8:9], v236
	v_readfirstlane_b32 s0, v66
	s_ashr_i32 s1, s0, 6
	s_lshl_b32 s0, s1, 1
	s_mul_i32 s3, s1, 0x1040
	s_mov_b32 s2, s97
	v_lshl_or_b32 v20, s1, 3, v16
	s_ashr_i32 s1, s0, 31
	v_add_u32_e32 v19, s3, v18
	s_waitcnt lgkmcnt(0)
	v_readfirstlane_b32 s3, v7
	s_waitcnt lgkmcnt(0)
	v_readfirstlane_b32 s96, v8
	s_lshl_b64 s[10:11], s[0:1], 12
	s_or_b64 s[2:3], s[96:97], s[2:3]
	s_add_u32 s2, s2, s10
	v_ashrrev_i32_e32 v21, 31, v20
	v_or_b32_e32 v22, 2, v20
	s_addc_u32 s3, s3, s11
	v_lshl_add_u32 v60, v20, 5, v17
	v_or_b32_e32 v32, 4, v20
	v_or_b32_e32 v34, 6, v20
	v_lshlrev_b64 v[20:21], 19, v[20:21]
	v_ashrrev_i32_e32 v23, 31, v22
	v_lshl_add_u64 v[40:41], s[2:3], 0, v[2:3]
	v_lshl_add_u32 v61, v22, 5, v17
	v_lshl_add_u64 v[36:37], v[0:1], 0, v[20:21]
	v_lshlrev_b64 v[38:39], 19, v[22:23]
	global_load_dwordx4 v[6:9], v[40:41], off
	global_load_dwordx4 v[20:23], v[40:41], off offset:1024
	global_load_dwordx4 v[24:27], v[40:41], off offset:3072
	global_load_dwordx4 v[28:31], v[40:41], off offset:2048
	s_lshl_b64 s[10:11], s[0:1], 11
	s_add_u32 s2, s38, s10
	s_addc_u32 s3, s39, s11
	v_add_co_u32_e32 v40, vcc, s13, v40
	v_lshl_add_u64 v[42:43], s[2:3], 0, v[4:5]
	s_nop 0
	v_addc_co_u32_e32 v41, vcc, 0, v41, vcc
	v_add_co_u32_e32 v42, vcc, s21, v42
	s_or_b32 s0, s0, 1
	s_nop 0
	v_addc_co_u32_e32 v43, vcc, 0, v43, vcc
	s_mulk_i32 s0, 0x820
	v_lshl_add_u32 v62, v32, 5, v17
	v_lshl_add_u32 v63, v34, 5, v17
	v_ashrrev_i32_e32 v33, 31, v32
	v_ashrrev_i32_e32 v35, 31, v34
	v_lshlrev_b64 v[32:33], 19, v[32:33]
	v_lshlrev_b64 v[34:35], 19, v[34:35]
	v_lshl_add_u64 v[36:37], s[38:39], 0, v[36:37]
	v_lshl_add_u64 v[38:39], v[0:1], 0, v[38:39]
	v_lshl_add_u64 v[32:33], v[0:1], 0, v[32:33]
	v_lshl_add_u64 v[34:35], v[0:1], 0, v[34:35]
	v_lshl_add_u64 v[38:39], s[38:39], 0, v[38:39]
	v_lshl_add_u64 v[32:33], s[38:39], 0, v[32:33]
	v_lshl_add_u64 v[34:35], s[38:39], 0, v[34:35]
	s_add_i32 s5, s5, s12
	v_lshl_add_u64 v[0:1], v[0:1], 0, s[14:15]
	v_lshl_add_u64 v[2:3], v[2:3], 0, s[18:19]
	v_lshl_add_u64 v[4:5], v[4:5], 0, s[16:17]
	s_cmpk_gt_i32 s5, 0x3ff
	s_waitcnt vmcnt(0)
	v_cvt_pk_bf16_f32 v56, v6, v7
	v_pk_mul_f32 v[44:45], v[8:9], v[8:9]
	v_pk_mul_f32 v[46:47], v[6:7], v[6:7]
	s_waitcnt vmcnt(2)
	v_pk_mul_f32 v[48:49], v[22:23], v[22:23]
	v_pk_mul_f32 v[50:51], v[20:21], v[20:21]
	v_pk_mov_b32 v[58:59], v[46:47], v[44:45] op_sel:[1,0]
	v_mov_b32_e32 v47, v45
	v_pk_mov_b32 v[44:45], v[50:51], v[48:49] op_sel:[1,0]
	v_mov_b32_e32 v51, v49
	s_waitcnt vmcnt(1)
	v_mul_f32_e32 v55, v24, v24
	s_waitcnt vmcnt(0)
	v_mul_f32_e32 v52, v29, v29
	v_mul_f32_e32 v54, v31, v31
	v_pk_add_f32 v[46:47], v[58:59], v[46:47]
	v_pk_add_f32 v[44:45], v[44:45], v[50:51]
	v_mul_f32_e32 v67, v25, v25
	v_mul_f32_e32 v68, v26, v26
	v_mul_f32_e32 v69, v27, v27
	v_pk_fma_f32 v[48:49], v[28:29], v[28:29], v[52:53] op_sel_hi:[1,1,0]
	v_pk_fma_f32 v[52:53], v[30:31], v[30:31], v[54:55] op_sel_hi:[1,1,0]
	v_pk_add_f32 v[46:47], v[46:47], v[46:47] op_sel:[0,1] op_sel_hi:[1,0]
	v_pk_add_f32 v[44:45], v[44:45], v[44:45] op_sel:[0,1] op_sel_hi:[1,0]
	v_mov_b32_e32 v49, v68
	v_mov_b32_e32 v53, v69
	v_mov_b32_e32 v47, v55
	v_mov_b32_e32 v45, v67
	v_pk_add_f32 v[48:49], v[48:49], v[52:53]
	v_pk_add_f32 v[44:45], v[46:47], v[44:45]
	v_cvt_pk_bf16_f32 v57, v8, v9
	global_store_dwordx2 v[42:43], v[56:57], off
	v_pk_add_f32 v[44:45], v[44:45], v[48:49]
	s_nop 0
	v_add_f32_e32 v44, v44, v45
	ds_bpermute_b32 v45, v10, v44
	s_waitcnt lgkmcnt(0)
	v_add_f32_e32 v44, v44, v45
	ds_bpermute_b32 v45, v11, v44
	s_waitcnt lgkmcnt(0)
	v_add_f32_e32 v44, v44, v45
	ds_bpermute_b32 v45, v12, v44
	s_waitcnt lgkmcnt(0)
	v_add_f32_e32 v44, v44, v45
	ds_bpermute_b32 v45, v13, v44
	s_waitcnt lgkmcnt(0)
	v_add_f32_e32 v44, v44, v45
	ds_bpermute_b32 v45, v14, v44
	s_waitcnt lgkmcnt(0)
	v_add_f32_e32 v44, v44, v45
	ds_bpermute_b32 v45, v15, v44
	s_waitcnt lgkmcnt(0)
; __device__ __forceinline__ unsigned cvt_pk_bf16(float lo, float hi) { unsigned r; asm volatile("v_cvt_pk_bf16_f32 %0, %1, %2" : "=v"(r) : "v"(lo), "v"(hi)); return r; }
; template <bool F32SRC> __device__ __forceinline__ void unorm_chunk(LAS unsigned char* lds, const float* xsrc, bf16_t* hbio, bf16_t* Ug, int chunk, const int tid) {
;     ...
;             const float rstd = rsqrtf(wsum_l(ss, lane) * (1.0f / DM) + EPS);
;             u32x2* o = (u32x2*)(hbio + row * DM) + lane;
; #pragma unroll
;             for (int j = 0; j < 4; ++j) { u32x2 w; w.x = pg8::cvt_pk_bf16(v[j].x, v[j].y); w.y = pg8::cvt_pk_bf16(v[j].z, v[j].w); o[64 * j] = w;
;                 u32x2 q; q.x = pg8::cvt_pk_bf16(v[j].x * rstd, v[j].y * rstd); q.y = pg8::cvt_pk_bf16(v[j].z * rstd, v[j].w * rstd); *(LAS u32x2*)(T + s * 2080 + (64 * j + lane) * 8) = q; }
;         } else { const u32x4* xr = (const u32x4*)(hbio + row * DM) + lane; u32x4 w[2]; float v[16]; float ss = 0.f;
; #pragma unroll
;             for (int j = 0; j < 2; ++j) { w[j] = xr[64 * j];
;                 v[8 * j + 0] = __uint_as_float(w[j].x << 16); v[8 * j + 1] = __uint_as_float(w[j].x & 0xffff0000u); v[8 * j + 2] = __uint_as_float(w[j].y << 16); v[8 * j + 3] = __uint_as_float(w[j].y & 0xffff0000u);
;                 v[8 * j + 4] = __uint_as_float(w[j].z << 16); v[8 * j + 5] = __uint_as_float(w[j].z & 0xffff0000u); v[8 * j + 6] = __uint_as_float(w[j].w << 16); v[8 * j + 7] = __uint_as_float(w[j].w & 0xffff0000u); }
; #pragma unroll
;             for (int i = 0; i < 16; ++i) ss += v[i] * v[i];
;             const float rstd = rsqrtf(wsum_l(ss, lane) * (1.0f / DM) + EPS);
; #pragma unroll
;             for (int j = 0; j < 2; ++j) { u32x4 q; q.x = pg8::cvt_pk_bf16(v[8 * j] * rstd, v[8 * j + 1] * rstd); q.y = pg8::cvt_pk_bf16(v[8 * j + 2] * rstd, v[8 * j + 3] * rstd);
;                 q.z = pg8::cvt_pk_bf16(v[8 * j + 4] * rstd, v[8 * j + 5] * rstd); q.w = pg8::cvt_pk_bf16(v[8 * j + 6] * rstd, v[8 * j + 7] * rstd); *(LAS u32x4*)(T + s * 2080 + (64 * j + lane) * 16) = q; } }
;     }
;     LDS_WAIT(); __syncthreads();
; #pragma unroll
;     for (int i = 0; i < 4; ++i) { const int gq = 8 * wid + 2 * i + (lane >> 5), l = lane & 31, s = l >> 1, hf = l & 1;
;         const u32x4 q = *(const LAS u32x4*)(T + s * 2080 + gq * 32 + hf * 16);
;         *(u32x4*)(Ug + ((size_t)gq * 1024 + chunk) * 256 + l * 8) = q; }
	v_add_f32_e32 v44, v44, v45
	v_fmamk_f32 v44, v44, 0x3a800000, v226
	v_mul_f32_e32 v45, 0x4b800000, v44
	v_cmp_gt_f32_e32 vcc, s24, v44
	s_nop 1
	v_cndmask_b32_e32 v44, v44, v45, vcc
	v_rsq_f32_e32 v44, v44
	s_nop 0
	v_mul_f32_e32 v45, 0x45800000, v44
	v_cndmask_b32_e32 v44, v44, v45, vcc
	v_mul_f32_e32 v6, v6, v44
	v_mul_f32_e32 v7, v7, v44
	v_mul_f32_e32 v8, v8, v44
	v_mul_f32_e32 v9, v9, v44
	v_cvt_pk_bf16_f32 v6, v6, v7
	v_cvt_pk_bf16_f32 v7, v8, v9
	ds_write_b64 v19, v[6:7]
	v_cvt_pk_bf16_f32 v6, v20, v21
	v_cvt_pk_bf16_f32 v7, v22, v23
	v_mul_f32_e32 v45, v20, v44
	v_mul_f32_e32 v46, v21, v44
	v_mul_f32_e32 v47, v22, v44
	v_mul_f32_e32 v48, v23, v44
	global_store_dwordx2 v[42:43], v[6:7], off offset:512
	v_cvt_pk_bf16_f32 v6, v45, v46
	v_cvt_pk_bf16_f32 v7, v47, v48
	ds_write_b64 v19, v[6:7] offset:512
	v_cvt_pk_bf16_f32 v6, v28, v29
	v_cvt_pk_bf16_f32 v7, v30, v31
	v_mul_f32_e32 v49, v28, v44
	v_mul_f32_e32 v50, v29, v44
	v_mul_f32_e32 v51, v30, v44
	v_mul_f32_e32 v52, v31, v44
	global_store_dwordx2 v[42:43], v[6:7], off offset:1024
	v_cvt_pk_bf16_f32 v6, v49, v50
	v_cvt_pk_bf16_f32 v7, v51, v52
	ds_write_b64 v19, v[6:7] offset:1024
	v_cvt_pk_bf16_f32 v6, v24, v25
	v_cvt_pk_bf16_f32 v7, v26, v27
	v_mul_f32_e32 v53, v24, v44
	v_mul_f32_e32 v54, v25, v44
	v_mul_f32_e32 v55, v26, v44
	v_mul_f32_e32 v56, v27, v44
	global_store_dwordx2 v[42:43], v[6:7], off offset:1536
	v_cvt_pk_bf16_f32 v44, v53, v54
	v_cvt_pk_bf16_f32 v45, v55, v56
	global_load_dwordx4 v[6:9], v[40:41], off
	global_load_dwordx4 v[20:23], v[40:41], off offset:1024
	global_load_dwordx4 v[24:27], v[40:41], off offset:2048
	global_load_dwordx4 v[28:31], v[40:41], off offset:3072
	ds_write_b64 v19, v[44:45] offset:1536
	v_add_u32_e32 v53, s0, v18
	s_waitcnt vmcnt(3)
	v_cvt_pk_bf16_f32 v54, v6, v7
	v_pk_mul_f32 v[40:41], v[8:9], v[8:9]
	v_pk_mul_f32 v[44:45], v[6:7], v[6:7]
	s_waitcnt vmcnt(2)
	v_pk_mul_f32 v[46:47], v[22:23], v[22:23]
	v_pk_mul_f32 v[48:49], v[20:21], v[20:21]
	v_pk_mov_b32 v[56:57], v[44:45], v[40:41] op_sel:[1,0]
	v_mov_b32_e32 v45, v41
	v_pk_mov_b32 v[40:41], v[48:49], v[46:47] op_sel:[1,0]
	v_mov_b32_e32 v49, v47
	s_waitcnt vmcnt(1)
	v_mul_f32_e32 v50, v25, v25
	v_mul_f32_e32 v52, v27, v27
	v_pk_add_f32 v[44:45], v[56:57], v[44:45]
	v_pk_add_f32 v[40:41], v[40:41], v[48:49]
	s_waitcnt vmcnt(0)
	v_mul_f32_e32 v19, v28, v28
	v_mul_f32_e32 v58, v29, v29
	v_mul_f32_e32 v59, v30, v30
	v_mul_f32_e32 v67, v31, v31
	v_pk_fma_f32 v[46:47], v[24:25], v[24:25], v[50:51] op_sel_hi:[1,1,0]
	v_pk_fma_f32 v[50:51], v[26:27], v[26:27], v[52:53] op_sel_hi:[1,1,0]
	v_pk_add_f32 v[44:45], v[44:45], v[44:45] op_sel:[0,1] op_sel_hi:[1,0]
	v_pk_add_f32 v[40:41], v[40:41], v[40:41] op_sel:[0,1] op_sel_hi:[1,0]
	v_mov_b32_e32 v47, v59
	v_mov_b32_e32 v51, v67
	v_mov_b32_e32 v45, v19
	v_mov_b32_e32 v41, v58
	v_pk_add_f32 v[46:47], v[46:47], v[50:51]
	v_pk_add_f32 v[40:41], v[44:45], v[40:41]
	v_cvt_pk_bf16_f32 v55, v8, v9
	global_store_dwordx2 v[42:43], v[54:55], off offset:2048
	v_pk_add_f32 v[40:41], v[40:41], v[46:47]
	s_nop 0
	v_add_f32_e32 v19, v40, v41
	ds_bpermute_b32 v40, v10, v19
	s_waitcnt lgkmcnt(0)
	v_add_f32_e32 v19, v19, v40
	ds_bpermute_b32 v40, v11, v19
	s_waitcnt lgkmcnt(0)
	v_add_f32_e32 v19, v19, v40
	ds_bpermute_b32 v40, v12, v19
	s_waitcnt lgkmcnt(0)
	v_add_f32_e32 v19, v19, v40
	ds_bpermute_b32 v40, v13, v19
	s_waitcnt lgkmcnt(0)
	v_add_f32_e32 v19, v19, v40
	ds_bpermute_b32 v40, v14, v19
	s_waitcnt lgkmcnt(0)
	v_add_f32_e32 v19, v19, v40
	ds_bpermute_b32 v40, v15, v19
	s_waitcnt lgkmcnt(0)
	v_add_f32_e32 v19, v19, v40
	v_fmamk_f32 v19, v19, 0x3a800000, v226
	v_mul_f32_e32 v40, 0x4b800000, v19
	v_cmp_gt_f32_e32 vcc, s24, v19
	s_nop 1
	v_cndmask_b32_e32 v19, v19, v40, vcc
	v_rsq_f32_e32 v19, v19
	s_nop 0
	v_mul_f32_e32 v40, 0x45800000, v19
	v_cndmask_b32_e32 v19, v19, v40, vcc
	v_mul_f32_e32 v6, v6, v19
	v_mul_f32_e32 v7, v7, v19
	v_mul_f32_e32 v8, v8, v19
	v_mul_f32_e32 v9, v9, v19
	v_cvt_pk_bf16_f32 v6, v6, v7
	v_cvt_pk_bf16_f32 v7, v8, v9
	ds_write_b64 v53, v[6:7]
	v_cvt_pk_bf16_f32 v6, v20, v21
	v_cvt_pk_bf16_f32 v7, v22, v23
	v_mul_f32_e32 v40, v20, v19
	v_mul_f32_e32 v41, v21, v19
	v_mul_f32_e32 v44, v22, v19
	v_mul_f32_e32 v45, v23, v19
	global_store_dwordx2 v[42:43], v[6:7], off offset:2560
	v_cvt_pk_bf16_f32 v6, v40, v41
	v_cvt_pk_bf16_f32 v7, v44, v45
	ds_write_b64 v53, v[6:7] offset:512
	v_cvt_pk_bf16_f32 v6, v24, v25
	v_cvt_pk_bf16_f32 v7, v26, v27
	v_mul_f32_e32 v46, v24, v19
	v_mul_f32_e32 v47, v25, v19
	v_mul_f32_e32 v48, v26, v19
	v_mul_f32_e32 v49, v27, v19
	global_store_dwordx2 v[42:43], v[6:7], off offset:3072
	v_cvt_pk_bf16_f32 v6, v46, v47
	v_cvt_pk_bf16_f32 v7, v48, v49
	ds_write_b64 v53, v[6:7] offset:1024
	v_cvt_pk_bf16_f32 v6, v28, v29
	v_cvt_pk_bf16_f32 v7, v30, v31
	v_mul_f32_e32 v50, v28, v19
	v_mul_f32_e32 v51, v29, v19
	v_mul_f32_e32 v52, v30, v19
	v_mul_f32_e32 v19, v31, v19
	global_store_dwordx2 v[42:43], v[6:7], off offset:3584
	v_cvt_pk_bf16_f32 v6, v50, v51
	v_cvt_pk_bf16_f32 v7, v52, v19
	ds_write_b64 v53, v[6:7] offset:1536
	s_waitcnt lgkmcnt(0)
	s_waitcnt lgkmcnt(0)
	s_barrier
	ds_read_b128 v[6:9], v60
	ds_read_b128 v[20:23], v61
	ds_read_b128 v[24:27], v62
	ds_read_b128 v[28:31], v63
	s_waitcnt lgkmcnt(3)
	global_store_dwordx4 v[36:37], v[6:9], off
	s_waitcnt lgkmcnt(2)
	global_store_dwordx4 v[38:39], v[20:23], off
	s_waitcnt lgkmcnt(1)
	global_store_dwordx4 v[32:33], v[24:27], off
	s_waitcnt lgkmcnt(0)
	global_store_dwordx4 v[34:35], v[28:31], off
	s_waitcnt lgkmcnt(0)
	s_barrier
	s_cbranch_scc0 .LBB0_312

; #define LAS __attribute__((address_space(3)))
; __device__ __forceinline__ void conv_item(const float* W, int ldw, int K, int c0, int k0, const float* gain, bf16_t* Wt, int n0, LAS float* scr, int lane) {
;     f32x4 v[16];
;     const int kr = lane >> 4, n4 = (lane & 15) * 4;
;     const float* src = W + (size_t)(k0 + kr) * ldw + c0 + n4;
; #pragma unroll
;     for (int i = 0; i < 16; ++i) v[i] = __builtin_nontemporal_load((const f32x4*)(src + (size_t)(4 * i) * ldw));
;     if (gain) {
; #pragma unroll
;         for (int i = 0; i < 16; ++i) v[i] = v[i] * gain[k0 + 4 * i + kr];
;     }
; __device__ __forceinline__ void conv_matrix(const float* W, int ldw, int K, int N, int kind, int arg, const float* gain, bf16_t* Wt, LAS float* scr, int lane, int gw, int NGW, int& rot) {
;     ...
;     for (int it = (gw + NGW - rot) % NGW; it < nitems; it += NGW) { const int kb = it / nblk, nb = it % nblk; conv_item(W, ldw, K, map_col(kind, arg, nb * 64), kb * 64, gain, Wt, nb * 64, scr, lane); }
.LBB0_325:
	s_ashr_i32 s16, s18, 31
	s_lshr_b32 s16, s16, 28
	s_add_i32 s16, s18, s16
	s_ashr_i32 s16, s16, 4
	s_lshl_b32 s17, s16, 10
	s_lshl_b32 s16, s16, 6
	v_or_b32_e32 v74, s16, v76
	v_ashrrev_i32_e32 v75, 31, v74
	s_sub_i32 s24, s19, s17
	v_lshlrev_b64 v[0:1], 12, v[74:75]
	v_lshl_add_u64 v[0:1], s[10:11], 0, v[0:1]
	s_ashr_i32 s25, s24, 31
	v_lshl_add_u64 v[0:1], s[24:25], 2, v[0:1]
	v_lshl_add_u64 v[56:57], v[0:1], 0, v[208:209]
	s_movk_i32 s24, 0x4000
	v_add_co_u32_e32 v4, vcc, s24, v56
	s_mov_b32 s24, 0x14000
	s_nop 0
	v_addc_co_u32_e32 v5, vcc, 0, v57, vcc
	v_add_co_u32_e32 v8, vcc, s26, v56
	global_load_dwordx4 v[0:3], v[56:57], off
	s_nop 0
	global_load_dwordx4 v[4:7], v[4:5], off
	v_addc_co_u32_e32 v9, vcc, 0, v57, vcc
	v_add_co_u32_e32 v12, vcc, s65, v56
	s_nop 1
	v_addc_co_u32_e32 v13, vcc, 0, v57, vcc
	v_add_co_u32_e32 v16, vcc, s27, v56
	global_load_dwordx4 v[8:11], v[8:9], off
	s_nop 0
	global_load_dwordx4 v[12:15], v[12:13], off
	v_addc_co_u32_e32 v17, vcc, 0, v57, vcc
	v_add_co_u32_e32 v20, vcc, s24, v56
	s_mov_b32 s24, 0x24000
	s_nop 0
	v_addc_co_u32_e32 v21, vcc, 0, v57, vcc
	v_add_co_u32_e32 v24, vcc, s28, v56
	global_load_dwordx4 v[16:19], v[16:17], off
	s_nop 0
	global_load_dwordx4 v[20:23], v[20:21], off
	v_addc_co_u32_e32 v25, vcc, 0, v57, vcc
	v_add_co_u32_e32 v28, vcc, s66, v56
	s_nop 1
	v_addc_co_u32_e32 v29, vcc, 0, v57, vcc
	v_add_co_u32_e32 v32, vcc, s29, v56
	global_load_dwordx4 v[24:27], v[24:25], off
	s_nop 0
	global_load_dwordx4 v[28:31], v[28:29], off
	v_addc_co_u32_e32 v33, vcc, 0, v57, vcc
	v_add_co_u32_e32 v36, vcc, s24, v56
	s_mov_b32 s24, 0x2c000
	s_nop 0
	v_addc_co_u32_e32 v37, vcc, 0, v57, vcc
	v_add_co_u32_e32 v40, vcc, s30, v56
	global_load_dwordx4 v[32:35], v[32:33], off
	s_nop 0
	global_load_dwordx4 v[36:39], v[36:37], off
	v_addc_co_u32_e32 v41, vcc, 0, v57, vcc
	v_add_co_u32_e32 v44, vcc, s24, v56
	s_nop 1
	v_addc_co_u32_e32 v45, vcc, 0, v57, vcc
	v_add_co_u32_e32 v48, vcc, s31, v56
	global_load_dwordx4 v[40:43], v[40:41], off
	s_nop 0
	global_load_dwordx4 v[44:47], v[44:45], off
	v_addc_co_u32_e32 v49, vcc, 0, v57, vcc
	v_add_co_u32_e32 v52, vcc, 0x34000, v56
	s_nop 1
	v_addc_co_u32_e32 v53, vcc, 0, v57, vcc
	v_add_co_u32_e32 v58, vcc, 0x38000, v56
	global_load_dwordx4 v[48:51], v[48:49], off
	s_nop 0
	global_load_dwordx4 v[52:55], v[52:53], off
	v_addc_co_u32_e32 v59, vcc, 0, v57, vcc
	v_add_co_u32_e32 v60, vcc, 0x3c000, v56
	s_nop 1
	v_addc_co_u32_e32 v61, vcc, 0, v57, vcc
	global_load_dwordx4 v[56:59], v[58:59], off
	s_nop 0
	global_load_dwordx4 v[60:63], v[60:61], off
	s_andn2_b64 vcc, exec, s[14:15]
	s_cbranch_vccnz .LBB0_324
	v_lshl_add_u64 v[74:75], v[74:75], 2, s[12:13]
	global_load_dword v102, v[74:75], off
	global_load_dword v104, v[74:75], off offset:16
	global_load_dword v106, v[74:75], off offset:32
	global_load_dword v108, v[74:75], off offset:48
	global_load_dword v110, v[74:75], off offset:64
	global_load_dword v112, v[74:75], off offset:80
	global_load_dword v114, v[74:75], off offset:96
	global_load_dword v116, v[74:75], off offset:112
	global_load_dword v118, v[74:75], off offset:128
	global_load_dword v120, v[74:75], off offset:144
	global_load_dword v122, v[74:75], off offset:160
	global_load_dword v124, v[74:75], off offset:176
	global_load_dword v126, v[74:75], off offset:192
	global_load_dword v128, v[74:75], off offset:208
	global_load_dword v130, v[74:75], off offset:224
	s_nop 0
	global_load_dword v74, v[74:75], off offset:240
	s_waitcnt vmcnt(0)
	v_pk_mul_f32 v[2:3], v[2:3], v[102:103] op_sel_hi:[1,0]
	v_pk_mul_f32 v[0:1], v[0:1], v[102:103] op_sel_hi:[1,0]
	s_waitcnt vmcnt(14)
	v_pk_mul_f32 v[6:7], v[6:7], v[104:105] op_sel_hi:[1,0]
	v_pk_mul_f32 v[4:5], v[4:5], v[104:105] op_sel_hi:[1,0]
	s_waitcnt vmcnt(13)
	v_pk_mul_f32 v[10:11], v[10:11], v[106:107] op_sel_hi:[1,0]
	v_pk_mul_f32 v[8:9], v[8:9], v[106:107] op_sel_hi:[1,0]
	s_waitcnt vmcnt(12)
	v_pk_mul_f32 v[14:15], v[14:15], v[108:109] op_sel_hi:[1,0]
	v_pk_mul_f32 v[12:13], v[12:13], v[108:109] op_sel_hi:[1,0]
	s_waitcnt vmcnt(11)
	v_pk_mul_f32 v[18:19], v[18:19], v[110:111] op_sel_hi:[1,0]
	v_pk_mul_f32 v[16:17], v[16:17], v[110:111] op_sel_hi:[1,0]
	s_waitcnt vmcnt(10)
	v_pk_mul_f32 v[22:23], v[22:23], v[112:113] op_sel_hi:[1,0]
	v_pk_mul_f32 v[20:21], v[20:21], v[112:113] op_sel_hi:[1,0]
	s_waitcnt vmcnt(9)
	v_pk_mul_f32 v[26:27], v[26:27], v[114:115] op_sel_hi:[1,0]
	v_pk_mul_f32 v[24:25], v[24:25], v[114:115] op_sel_hi:[1,0]
	s_waitcnt vmcnt(8)
	v_pk_mul_f32 v[30:31], v[30:31], v[116:117] op_sel_hi:[1,0]
	v_pk_mul_f32 v[28:29], v[28:29], v[116:117] op_sel_hi:[1,0]
	s_waitcnt vmcnt(7)
	v_pk_mul_f32 v[34:35], v[34:35], v[118:119] op_sel_hi:[1,0]
	v_pk_mul_f32 v[32:33], v[32:33], v[118:119] op_sel_hi:[1,0]
	s_waitcnt vmcnt(6)
	v_pk_mul_f32 v[38:39], v[38:39], v[120:121] op_sel_hi:[1,0]
	v_pk_mul_f32 v[36:37], v[36:37], v[120:121] op_sel_hi:[1,0]
	s_waitcnt vmcnt(5)
	v_pk_mul_f32 v[42:43], v[42:43], v[122:123] op_sel_hi:[1,0]
	v_pk_mul_f32 v[40:41], v[40:41], v[122:123] op_sel_hi:[1,0]
	s_waitcnt vmcnt(4)
	v_pk_mul_f32 v[46:47], v[46:47], v[124:125] op_sel_hi:[1,0]
	v_pk_mul_f32 v[44:45], v[44:45], v[124:125] op_sel_hi:[1,0]
	s_waitcnt vmcnt(3)
	v_pk_mul_f32 v[50:51], v[50:51], v[126:127] op_sel_hi:[1,0]
	v_pk_mul_f32 v[48:49], v[48:49], v[126:127] op_sel_hi:[1,0]
	s_waitcnt vmcnt(2)
	v_pk_mul_f32 v[54:55], v[54:55], v[128:129] op_sel_hi:[1,0]
	v_pk_mul_f32 v[52:53], v[52:53], v[128:129] op_sel_hi:[1,0]
	s_waitcnt vmcnt(1)
	v_pk_mul_f32 v[58:59], v[58:59], v[130:131] op_sel_hi:[1,0]
	v_pk_mul_f32 v[56:57], v[56:57], v[130:131] op_sel_hi:[1,0]
	s_waitcnt vmcnt(0)
	v_pk_mul_f32 v[62:63], v[62:63], v[74:75] op_sel_hi:[1,0]
	v_pk_mul_f32 v[60:61], v[60:61], v[74:75] op_sel_hi:[1,0]
	s_branch .LBB0_324

; #define LAS __attribute__((address_space(3)))
; __device__ __forceinline__ void conv_item(const float* W, int ldw, int K, int c0, int k0, const float* gain, bf16_t* Wt, int n0, LAS float* scr, int lane) {
;     f32x4 v[16];
;     const int kr = lane >> 4, n4 = (lane & 15) * 4;
;     const float* src = W + (size_t)(k0 + kr) * ldw + c0 + n4;
; #pragma unroll
;     for (int i = 0; i < 16; ++i) v[i] = __builtin_nontemporal_load((const f32x4*)(src + (size_t)(4 * i) * ldw));
;     if (gain) {
; #pragma unroll
;         for (int i = 0; i < 16; ++i) v[i] = v[i] * gain[k0 + 4 * i + kr];
;     }
; #pragma unroll
;     for (int i = 0; i < 16; ++i) { const int k = 4 * i + kr; *(LAS f32x4*)(scr + k * 64 + (n4 ^ (((k >> 3) & 7) << 2))) = v[i]; }
; __device__ __forceinline__ void conv_matrix(const float* W, int ldw, int K, int N, int kind, int arg, const float* gain, bf16_t* Wt, LAS float* scr, int lane, int gw, int NGW, int& rot) {
;     ...
;     for (int it = (gw + NGW - rot) % NGW; it < nitems; it += NGW) { const int kb = it / nblk, nb = it % nblk; conv_item(W, ldw, K, map_col(kind, arg, nb * 64), kb * 64, gain, Wt, nb * 64, scr, lane); }
.LBB0_329:
	s_ashr_i32 s10, s15, 31
	s_lshr_b32 s10, s10, 28
	s_add_i32 s10, s15, s10
	s_ashr_i32 s10, s10, 4
	s_lshl_b32 s12, s10, 6
	v_or_b32_e32 v0, s12, v76
	s_lshl_b32 s11, s10, 10
	v_ashrrev_i32_e32 v1, 31, v0
	s_sub_i32 s10, s16, s11
	v_lshlrev_b64 v[0:1], 12, v[0:1]
	s_ashr_i32 s11, s10, 31
	v_lshl_add_u64 v[0:1], s[2:3], 0, v[0:1]
	v_lshl_add_u64 v[0:1], s[10:11], 2, v[0:1]
	v_lshl_add_u64 v[0:1], v[0:1], 0, v[208:209]
	v_add_co_u32_e32 v6, vcc, s19, v0
	s_ashr_i32 s13, s12, 31
	s_nop 0
	v_addc_co_u32_e32 v7, vcc, 0, v1, vcc
	v_add_co_u32_e32 v8, vcc, s20, v0
	s_add_i32 s15, s15, s18
	s_nop 0
	v_addc_co_u32_e32 v9, vcc, 0, v1, vcc
	v_add_co_u32_e32 v34, vcc, s21, v0
	s_add_i32 s16, s16, s17
	s_nop 0
	v_addc_co_u32_e32 v35, vcc, 0, v1, vcc
	v_add_co_u32_e32 v38, vcc, s24, v0
	s_cmpk_lt_i32 s15, 0x100
	s_nop 0
	v_addc_co_u32_e32 v39, vcc, 0, v1, vcc
	v_add_co_u32_e32 v42, vcc, s25, v0
	s_nop 1
	v_addc_co_u32_e32 v43, vcc, 0, v1, vcc
	v_add_co_u32_e32 v46, vcc, s26, v0
	s_nop 1
	v_addc_co_u32_e32 v47, vcc, 0, v1, vcc
	v_add_co_u32_e32 v50, vcc, s27, v0
	s_nop 1
	v_addc_co_u32_e32 v51, vcc, 0, v1, vcc
	v_add_co_u32_e32 v54, vcc, s28, v0
	s_nop 1
	v_addc_co_u32_e32 v55, vcc, 0, v1, vcc
	v_add_co_u32_e32 v58, vcc, s29, v0
	s_nop 1
	v_addc_co_u32_e32 v59, vcc, 0, v1, vcc
	v_add_co_u32_e32 v62, vcc, s30, v0
	s_nop 1
	v_addc_co_u32_e32 v63, vcc, 0, v1, vcc
	v_add_co_u32_e32 v86, vcc, s31, v0
	s_nop 1
	v_addc_co_u32_e32 v87, vcc, 0, v1, vcc
	v_add_co_u32_e32 v90, vcc, s35, v0
	s_nop 1
	v_addc_co_u32_e32 v91, vcc, 0, v1, vcc
	v_add_co_u32_e32 v94, vcc, s36, v0
	s_nop 1
	v_addc_co_u32_e32 v95, vcc, 0, v1, vcc
	v_add_co_u32_e32 v98, vcc, s37, v0
	s_nop 1
	v_addc_co_u32_e32 v99, vcc, 0, v1, vcc
	v_add_co_u32_e32 v102, vcc, s38, v0
	s_nop 1
	v_addc_co_u32_e32 v103, vcc, 0, v1, vcc
	global_load_dwordx4 v[0:3], v[0:1], off
	s_nop 0
	global_load_dwordx4 v[26:29], v[6:7], off
	global_load_dwordx4 v[30:33], v[8:9], off
	s_nop 0
	global_load_dwordx4 v[34:37], v[34:35], off
	s_nop 0
	global_load_dwordx4 v[38:41], v[38:39], off
	s_nop 0
	global_load_dwordx4 v[42:45], v[42:43], off
	s_nop 0
	global_load_dwordx4 v[46:49], v[46:47], off
	s_nop 0
	global_load_dwordx4 v[50:53], v[50:51], off
	s_nop 0
	global_load_dwordx4 v[54:57], v[54:55], off
	s_nop 0
	global_load_dwordx4 v[58:61], v[58:59], off
	s_nop 0
	global_load_dwordx4 v[72:75], v[62:63], off
	s_nop 0
	global_load_dwordx4 v[86:89], v[86:87], off
	s_nop 0
	global_load_dwordx4 v[90:93], v[90:91], off
	s_nop 0
	global_load_dwordx4 v[94:97], v[94:95], off
	s_nop 0
	global_load_dwordx4 v[98:101], v[98:99], off
	s_nop 0
	global_load_dwordx4 v[102:105], v[102:103], off
	v_add_u32_e32 v8, s10, v65
	v_ashrrev_i32_e32 v9, 31, v8
	v_lshl_add_u64 v[6:7], s[12:13], 1, v[4:5]
	v_lshlrev_b64 v[116:117], 11, v[8:9]
	v_add_u32_e32 v62, 8, v8
	v_lshl_add_u64 v[116:117], v[6:7], 0, v[116:117]
	v_ashrrev_i32_e32 v63, 31, v62
	v_lshlrev_b64 v[62:63], 11, v[62:63]
	v_add_u32_e32 v106, 16, v8
	v_lshl_add_u64 v[62:63], v[6:7], 0, v[62:63]
	v_ashrrev_i32_e32 v107, 31, v106
	v_lshlrev_b64 v[106:107], 11, v[106:107]
	v_add_u32_e32 v108, 24, v8
	v_lshl_add_u64 v[106:107], v[6:7], 0, v[106:107]
	v_ashrrev_i32_e32 v109, 31, v108
	v_lshlrev_b64 v[108:109], 11, v[108:109]
	v_add_u32_e32 v110, 32, v8
	v_lshl_add_u64 v[108:109], v[6:7], 0, v[108:109]
	v_ashrrev_i32_e32 v111, 31, v110
	v_lshlrev_b64 v[110:111], 11, v[110:111]
	v_add_u32_e32 v112, 40, v8
	v_lshl_add_u64 v[110:111], v[6:7], 0, v[110:111]
	v_ashrrev_i32_e32 v113, 31, v112
	v_lshlrev_b64 v[112:113], 11, v[112:113]
	v_add_u32_e32 v114, 48, v8
	v_lshl_add_u64 v[112:113], v[6:7], 0, v[112:113]
	v_ashrrev_i32_e32 v115, 31, v114
	v_lshlrev_b64 v[114:115], 11, v[114:115]
	v_add_u32_e32 v8, 56, v8
	v_lshl_add_u64 v[114:115], v[6:7], 0, v[114:115]
	v_ashrrev_i32_e32 v9, 31, v8
	s_waitcnt vmcnt(0)
	ds_write_b128 v10, v[0:3]
	s_waitcnt vmcnt(14)
	ds_write_b128 v10, v[26:29] offset:1024
	s_waitcnt vmcnt(13)
	ds_write_b128 v11, v[30:33] offset:2048
	s_waitcnt vmcnt(12)
	ds_write_b128 v11, v[34:37] offset:3072
	s_waitcnt vmcnt(11)
	ds_write_b128 v12, v[38:41] offset:4096
	s_waitcnt vmcnt(10)
	ds_write_b128 v12, v[42:45] offset:5120
	s_waitcnt vmcnt(9)
	ds_write_b128 v13, v[46:49] offset:6144
	s_waitcnt vmcnt(8)
	ds_write_b128 v13, v[50:53] offset:7168
	s_waitcnt vmcnt(7)
	ds_write_b128 v14, v[54:57] offset:8192
	s_waitcnt vmcnt(6)
; __device__ __forceinline__ unsigned cvt_pk_bf16(float lo, float hi) { unsigned r; asm volatile("v_cvt_pk_bf16_f32 %0, %1, %2" : "=v"(r) : "v"(lo), "v"(hi)); return r; }
; #define LAS __attribute__((address_space(3)))
; #define LDS_WAIT() asm volatile("s_waitcnt lgkmcnt(0)" ::: "memory")
; __device__ __forceinline__ void conv_item(const float* W, int ldw, int K, int c0, int k0, const float* gain, bf16_t* Wt, int n0, LAS float* scr, int lane) {
;     ...
;     for (int i = 0; i < 16; ++i) { const int k = 4 * i + kr; *(LAS f32x4*)(scr + k * 64 + (n4 ^ (((k >> 3) & 7) << 2))) = v[i]; }
;     LDS_WAIT(); asm volatile("" ::: "memory");
;     const int c = lane & 7;
; #pragma unroll
;     for (int j = 0; j < 8; ++j) { const int n = (lane >> 3) + 8 * j; const LAS float* s = scr + (8 * c) * 64 + (n ^ (c << 2));
;         u32x4 o; o.x = pg8::cvt_pk_bf16(s[0 * 64], s[1 * 64]); o.y = pg8::cvt_pk_bf16(s[2 * 64], s[3 * 64]); o.z = pg8::cvt_pk_bf16(s[4 * 64], s[5 * 64]); o.w = pg8::cvt_pk_bf16(s[6 * 64], s[7 * 64]);
;         *(u32x4*)(Wt + (size_t)(n0 + n) * K + k0 + 8 * c) = o; }
;     LDS_WAIT(); asm volatile("" ::: "memory");
	ds_write_b128 v14, v[58:61] offset:9216
	s_waitcnt vmcnt(5)
	ds_write_b128 v15, v[72:75] offset:10240
	s_waitcnt vmcnt(4)
	ds_write_b128 v15, v[86:89] offset:11264
	s_waitcnt vmcnt(3)
	ds_write_b128 v16, v[90:93] offset:12288
	s_waitcnt vmcnt(2)
	ds_write_b128 v16, v[94:97] offset:13312
	s_waitcnt vmcnt(1)
	ds_write_b128 v17, v[98:101] offset:14336
	s_waitcnt vmcnt(0)
	ds_write_b128 v17, v[102:105] offset:15360
	s_waitcnt lgkmcnt(0)
	ds_read2st64_b32 v[0:1], v18 offset1:1
	s_waitcnt lgkmcnt(0)
	v_cvt_pk_bf16_f32 v0, v0, v1
	ds_read2st64_b32 v[2:3], v18 offset0:2 offset1:3
	s_waitcnt lgkmcnt(0)
	v_cvt_pk_bf16_f32 v1, v2, v3
	ds_read2st64_b32 v[2:3], v18 offset0:4 offset1:5
	s_waitcnt lgkmcnt(0)
	v_cvt_pk_bf16_f32 v2, v2, v3
	ds_read2st64_b32 v[26:27], v18 offset0:6 offset1:7
	s_waitcnt lgkmcnt(0)
	v_cvt_pk_bf16_f32 v3, v26, v27
	ds_read2st64_b32 v[26:27], v19 offset1:1
	global_store_dwordx4 v[116:117], v[0:3], off
	v_lshlrev_b64 v[8:9], 11, v[8:9]
	v_lshl_add_u64 v[6:7], v[6:7], 0, v[8:9]
	s_waitcnt lgkmcnt(0)
	v_cvt_pk_bf16_f32 v0, v26, v27
	ds_read2st64_b32 v[2:3], v19 offset0:2 offset1:3
	s_waitcnt lgkmcnt(0)
	v_cvt_pk_bf16_f32 v1, v2, v3
	ds_read2st64_b32 v[2:3], v19 offset0:4 offset1:5
	s_waitcnt lgkmcnt(0)
	v_cvt_pk_bf16_f32 v2, v2, v3
	ds_read2st64_b32 v[26:27], v19 offset0:6 offset1:7
	s_waitcnt lgkmcnt(0)
	v_cvt_pk_bf16_f32 v3, v26, v27
	ds_read2st64_b32 v[26:27], v20 offset1:1
	global_store_dwordx4 v[62:63], v[0:3], off
	s_waitcnt lgkmcnt(0)
	s_nop 0
	v_cvt_pk_bf16_f32 v0, v26, v27
	ds_read2st64_b32 v[2:3], v20 offset0:2 offset1:3
	s_waitcnt lgkmcnt(0)
	v_cvt_pk_bf16_f32 v1, v2, v3
	ds_read2st64_b32 v[2:3], v20 offset0:4 offset1:5
	s_waitcnt lgkmcnt(0)
	v_cvt_pk_bf16_f32 v2, v2, v3
	ds_read2st64_b32 v[26:27], v20 offset0:6 offset1:7
	s_waitcnt lgkmcnt(0)
	v_cvt_pk_bf16_f32 v3, v26, v27
	ds_read2st64_b32 v[26:27], v21 offset1:1
	global_store_dwordx4 v[106:107], v[0:3], off
	s_waitcnt lgkmcnt(0)
	s_nop 0
	v_cvt_pk_bf16_f32 v0, v26, v27
	ds_read2st64_b32 v[2:3], v21 offset0:2 offset1:3
	s_waitcnt lgkmcnt(0)
	v_cvt_pk_bf16_f32 v1, v2, v3
	ds_read2st64_b32 v[2:3], v21 offset0:4 offset1:5
	s_waitcnt lgkmcnt(0)
	v_cvt_pk_bf16_f32 v2, v2, v3
	ds_read2st64_b32 v[26:27], v21 offset0:6 offset1:7
	s_waitcnt lgkmcnt(0)
	v_cvt_pk_bf16_f32 v3, v26, v27
	ds_read2st64_b32 v[26:27], v22 offset1:1
	global_store_dwordx4 v[108:109], v[0:3], off
	s_waitcnt lgkmcnt(0)
	s_nop 0
	v_cvt_pk_bf16_f32 v0, v26, v27
	ds_read2st64_b32 v[2:3], v22 offset0:2 offset1:3
	s_waitcnt lgkmcnt(0)
	v_cvt_pk_bf16_f32 v1, v2, v3
	ds_read2st64_b32 v[2:3], v22 offset0:4 offset1:5
	s_waitcnt lgkmcnt(0)
	v_cvt_pk_bf16_f32 v2, v2, v3
	ds_read2st64_b32 v[26:27], v22 offset0:6 offset1:7
	s_waitcnt lgkmcnt(0)
	v_cvt_pk_bf16_f32 v3, v26, v27
	ds_read2st64_b32 v[26:27], v23 offset1:1
	global_store_dwordx4 v[110:111], v[0:3], off
	s_waitcnt lgkmcnt(0)
	s_nop 0
	v_cvt_pk_bf16_f32 v0, v26, v27
	ds_read2st64_b32 v[2:3], v23 offset0:2 offset1:3
	s_waitcnt lgkmcnt(0)
	v_cvt_pk_bf16_f32 v1, v2, v3
	ds_read2st64_b32 v[2:3], v23 offset0:4 offset1:5
	s_waitcnt lgkmcnt(0)
	v_cvt_pk_bf16_f32 v2, v2, v3
	ds_read2st64_b32 v[26:27], v23 offset0:6 offset1:7
	s_waitcnt lgkmcnt(0)
	v_cvt_pk_bf16_f32 v3, v26, v27
	ds_read2st64_b32 v[26:27], v24 offset1:1
	global_store_dwordx4 v[112:113], v[0:3], off
	s_waitcnt lgkmcnt(0)
	s_nop 0
	v_cvt_pk_bf16_f32 v0, v26, v27
	ds_read2st64_b32 v[2:3], v24 offset0:2 offset1:3
	s_waitcnt lgkmcnt(0)
	v_cvt_pk_bf16_f32 v1, v2, v3
	ds_read2st64_b32 v[2:3], v24 offset0:4 offset1:5
	s_waitcnt lgkmcnt(0)
	v_cvt_pk_bf16_f32 v2, v2, v3
	ds_read2st64_b32 v[26:27], v24 offset0:6 offset1:7
	s_waitcnt lgkmcnt(0)
	v_cvt_pk_bf16_f32 v3, v26, v27
	ds_read2st64_b32 v[26:27], v25 offset1:1
	global_store_dwordx4 v[114:115], v[0:3], off
	s_waitcnt lgkmcnt(0)
	s_nop 0
	v_cvt_pk_bf16_f32 v0, v26, v27
	ds_read2st64_b32 v[2:3], v25 offset0:2 offset1:3
	s_waitcnt lgkmcnt(0)
	v_cvt_pk_bf16_f32 v1, v2, v3
	ds_read2st64_b32 v[2:3], v25 offset0:4 offset1:5
	s_waitcnt lgkmcnt(0)
	v_cvt_pk_bf16_f32 v2, v2, v3
	ds_read2st64_b32 v[26:27], v25 offset0:6 offset1:7
	s_waitcnt lgkmcnt(0)
	v_cvt_pk_bf16_f32 v3, v26, v27
	global_store_dwordx4 v[6:7], v[0:3], off
	s_waitcnt lgkmcnt(0)
	s_cbranch_scc1 .LBB0_329
	s_mov_b32 s31, 0x30000
	s_mov_b32 s29, 0x20000
	s_mov_b32 s27, 0x10000
	s_mov_b32 s26, 0x8000

; #define LAS __attribute__((address_space(3)))
; __device__ __forceinline__ void conv_item(const float* W, int ldw, int K, int c0, int k0, const float* gain, bf16_t* Wt, int n0, LAS float* scr, int lane) {
;     f32x4 v[16];
;     const int kr = lane >> 4, n4 = (lane & 15) * 4;
;     const float* src = W + (size_t)(k0 + kr) * ldw + c0 + n4;
; #pragma unroll
;     for (int i = 0; i < 16; ++i) v[i] = __builtin_nontemporal_load((const f32x4*)(src + (size_t)(4 * i) * ldw));
;     if (gain) {
; #pragma unroll
;         for (int i = 0; i < 16; ++i) v[i] = v[i] * gain[k0 + 4 * i + kr];
;     }
.LBB0_334:
	s_ashr_i32 s14, s5, 31
	s_lshr_b32 s14, s14, 26
	s_add_i32 s14, s5, s14
	s_lshl_b32 s15, s14, 6
	s_andn2_b32 s14, s14, 63
	v_or_b32_e32 v74, s14, v76
	s_and_b32 s15, s15, 0xfffff000
	v_ashrrev_i32_e32 v75, 31, v74
	s_sub_i32 s20, s17, s15
	v_lshlrev_b64 v[0:1], 14, v[74:75]
	v_lshl_add_u64 v[0:1], s[10:11], 0, v[0:1]
	s_ashr_i32 s21, s20, 31
	v_lshl_add_u64 v[0:1], s[20:21], 2, v[0:1]
	v_lshl_add_u64 v[56:57], v[0:1], 0, v[208:209]
	v_add_co_u32_e32 v4, vcc, s27, v56
	s_mov_b32 s19, 0x80000
	s_nop 0
	v_addc_co_u32_e32 v5, vcc, 0, v57, vcc
	v_add_co_u32_e32 v8, vcc, s29, v56
	global_load_dwordx4 v[0:3], v[56:57], off
	s_nop 0
	global_load_dwordx4 v[4:7], v[4:5], off
	v_addc_co_u32_e32 v9, vcc, 0, v57, vcc
	v_add_co_u32_e32 v12, vcc, s31, v56
	s_nop 1
	v_addc_co_u32_e32 v13, vcc, 0, v57, vcc
	v_add_co_u32_e32 v16, vcc, s40, v56
	global_load_dwordx4 v[8:11], v[8:9], off
	s_nop 0
	global_load_dwordx4 v[12:15], v[12:13], off
	v_addc_co_u32_e32 v17, vcc, 0, v57, vcc
	v_add_co_u32_e32 v20, vcc, s41, v56
	s_nop 1
	v_addc_co_u32_e32 v21, vcc, 0, v57, vcc
	v_add_co_u32_e32 v24, vcc, s42, v56
	global_load_dwordx4 v[16:19], v[16:17], off
	s_nop 0
	global_load_dwordx4 v[20:23], v[20:21], off
	v_addc_co_u32_e32 v25, vcc, 0, v57, vcc
	v_add_co_u32_e32 v28, vcc, s43, v56
	s_nop 1
	v_addc_co_u32_e32 v29, vcc, 0, v57, vcc
	v_add_co_u32_e32 v32, vcc, s19, v56
	s_mov_b32 s19, 0x90000
	s_nop 0
	v_addc_co_u32_e32 v33, vcc, 0, v57, vcc
	v_add_co_u32_e32 v36, vcc, s19, v56
	s_mov_b32 s19, 0xa0000
	s_nop 0
	v_addc_co_u32_e32 v37, vcc, 0, v57, vcc
	v_add_co_u32_e32 v40, vcc, s19, v56
	s_mov_b32 s19, 0xb0000
	s_nop 0
	v_addc_co_u32_e32 v41, vcc, 0, v57, vcc
	v_add_co_u32_e32 v44, vcc, s19, v56
	s_mov_b32 s19, 0xc0000
	s_nop 0
	v_addc_co_u32_e32 v45, vcc, 0, v57, vcc
	v_add_co_u32_e32 v48, vcc, s19, v56
	global_load_dwordx4 v[24:27], v[24:25], off
	s_nop 0
	global_load_dwordx4 v[28:31], v[28:29], off
	v_addc_co_u32_e32 v49, vcc, 0, v57, vcc
	v_add_co_u32_e32 v52, vcc, 0xd0000, v56
	global_load_dwordx4 v[32:35], v[32:33], off
	s_nop 0
	global_load_dwordx4 v[36:39], v[36:37], off
	v_addc_co_u32_e32 v53, vcc, 0, v57, vcc
	v_add_co_u32_e32 v58, vcc, 0xe0000, v56
	global_load_dwordx4 v[40:43], v[40:41], off
	s_nop 0
	global_load_dwordx4 v[44:47], v[44:45], off
	v_addc_co_u32_e32 v59, vcc, 0, v57, vcc
	v_add_co_u32_e32 v60, vcc, 0xf0000, v56
	global_load_dwordx4 v[48:51], v[48:49], off
	s_nop 0
	global_load_dwordx4 v[52:55], v[52:53], off
	v_addc_co_u32_e32 v61, vcc, 0, v57, vcc
	global_load_dwordx4 v[56:59], v[58:59], off
	s_nop 0
	global_load_dwordx4 v[60:63], v[60:61], off
	s_andn2_b64 vcc, exec, s[12:13]
	s_cbranch_vccnz .LBB0_333
	v_lshl_add_u64 v[74:75], v[74:75], 2, s[0:1]
	global_load_dword v102, v[74:75], off
	global_load_dword v104, v[74:75], off offset:16
	global_load_dword v106, v[74:75], off offset:32
	global_load_dword v108, v[74:75], off offset:48
	global_load_dword v110, v[74:75], off offset:64
	global_load_dword v112, v[74:75], off offset:80
	global_load_dword v114, v[74:75], off offset:96
	global_load_dword v116, v[74:75], off offset:112
	global_load_dword v118, v[74:75], off offset:128
	global_load_dword v120, v[74:75], off offset:144
	global_load_dword v122, v[74:75], off offset:160
	global_load_dword v124, v[74:75], off offset:176
	global_load_dword v126, v[74:75], off offset:192
	global_load_dword v128, v[74:75], off offset:208
	global_load_dword v130, v[74:75], off offset:224
	s_nop 0
	global_load_dword v74, v[74:75], off offset:240
	s_waitcnt vmcnt(0)
	v_pk_mul_f32 v[2:3], v[2:3], v[102:103] op_sel_hi:[1,0]
	v_pk_mul_f32 v[0:1], v[0:1], v[102:103] op_sel_hi:[1,0]
	s_waitcnt vmcnt(14)
	v_pk_mul_f32 v[6:7], v[6:7], v[104:105] op_sel_hi:[1,0]
	v_pk_mul_f32 v[4:5], v[4:5], v[104:105] op_sel_hi:[1,0]
	s_waitcnt vmcnt(13)
	v_pk_mul_f32 v[10:11], v[10:11], v[106:107] op_sel_hi:[1,0]
	v_pk_mul_f32 v[8:9], v[8:9], v[106:107] op_sel_hi:[1,0]
	s_waitcnt vmcnt(12)
	v_pk_mul_f32 v[14:15], v[14:15], v[108:109] op_sel_hi:[1,0]
	v_pk_mul_f32 v[12:13], v[12:13], v[108:109] op_sel_hi:[1,0]
	s_waitcnt vmcnt(11)
	v_pk_mul_f32 v[18:19], v[18:19], v[110:111] op_sel_hi:[1,0]
	v_pk_mul_f32 v[16:17], v[16:17], v[110:111] op_sel_hi:[1,0]
	s_waitcnt vmcnt(10)
	v_pk_mul_f32 v[22:23], v[22:23], v[112:113] op_sel_hi:[1,0]
	v_pk_mul_f32 v[20:21], v[20:21], v[112:113] op_sel_hi:[1,0]
	s_waitcnt vmcnt(9)
	v_pk_mul_f32 v[26:27], v[26:27], v[114:115] op_sel_hi:[1,0]
	v_pk_mul_f32 v[24:25], v[24:25], v[114:115] op_sel_hi:[1,0]
	s_waitcnt vmcnt(8)
	v_pk_mul_f32 v[30:31], v[30:31], v[116:117] op_sel_hi:[1,0]
	v_pk_mul_f32 v[28:29], v[28:29], v[116:117] op_sel_hi:[1,0]
	s_waitcnt vmcnt(7)
	v_pk_mul_f32 v[34:35], v[34:35], v[118:119] op_sel_hi:[1,0]
	v_pk_mul_f32 v[32:33], v[32:33], v[118:119] op_sel_hi:[1,0]
	s_waitcnt vmcnt(6)
	v_pk_mul_f32 v[38:39], v[38:39], v[120:121] op_sel_hi:[1,0]
	v_pk_mul_f32 v[36:37], v[36:37], v[120:121] op_sel_hi:[1,0]
	s_waitcnt vmcnt(5)
	v_pk_mul_f32 v[42:43], v[42:43], v[122:123] op_sel_hi:[1,0]
	v_pk_mul_f32 v[40:41], v[40:41], v[122:123] op_sel_hi:[1,0]
	s_waitcnt vmcnt(4)
	v_pk_mul_f32 v[46:47], v[46:47], v[124:125] op_sel_hi:[1,0]
	v_pk_mul_f32 v[44:45], v[44:45], v[124:125] op_sel_hi:[1,0]
	s_waitcnt vmcnt(3)
	v_pk_mul_f32 v[50:51], v[50:51], v[126:127] op_sel_hi:[1,0]
	v_pk_mul_f32 v[48:49], v[48:49], v[126:127] op_sel_hi:[1,0]
	s_waitcnt vmcnt(2)
	v_pk_mul_f32 v[54:55], v[54:55], v[128:129] op_sel_hi:[1,0]
	v_pk_mul_f32 v[52:53], v[52:53], v[128:129] op_sel_hi:[1,0]
	s_waitcnt vmcnt(1)
	v_pk_mul_f32 v[58:59], v[58:59], v[130:131] op_sel_hi:[1,0]
	v_pk_mul_f32 v[56:57], v[56:57], v[130:131] op_sel_hi:[1,0]
	s_waitcnt vmcnt(0)
	v_pk_mul_f32 v[62:63], v[62:63], v[74:75] op_sel_hi:[1,0]
	v_pk_mul_f32 v[60:61], v[60:61], v[74:75] op_sel_hi:[1,0]
	s_branch .LBB0_333

; #define LAS __attribute__((address_space(3)))
; __device__ __forceinline__ void conv_item(const float* W, int ldw, int K, int c0, int k0, const float* gain, bf16_t* Wt, int n0, LAS float* scr, int lane) {
;     f32x4 v[16];
;     const int kr = lane >> 4, n4 = (lane & 15) * 4;
;     const float* src = W + (size_t)(k0 + kr) * ldw + c0 + n4;
; #pragma unroll
;     for (int i = 0; i < 16; ++i) v[i] = __builtin_nontemporal_load((const f32x4*)(src + (size_t)(4 * i) * ldw));
;     if (gain) {
; #pragma unroll
;         for (int i = 0; i < 16; ++i) v[i] = v[i] * gain[k0 + 4 * i + kr];
;     }
; #pragma unroll
;     for (int i = 0; i < 16; ++i) { const int k = 4 * i + kr; *(LAS f32x4*)(scr + k * 64 + (n4 ^ (((k >> 3) & 7) << 2))) = v[i]; }
.LBB0_338:
	s_ashr_i32 s2, s12, 31
	s_lshr_b32 s2, s2, 28
	s_add_i32 s2, s12, s2
	s_ashr_i32 s2, s2, 4
	s_lshl_b32 s10, s2, 6
	v_or_b32_e32 v0, s10, v76
	s_lshl_b32 s3, s2, 10
	v_ashrrev_i32_e32 v1, 31, v0
	s_sub_i32 s2, s13, s3
	v_lshlrev_b64 v[0:1], 12, v[0:1]
	s_ashr_i32 s3, s2, 31
	v_lshl_add_u64 v[0:1], s[0:1], 0, v[0:1]
	v_lshl_add_u64 v[0:1], s[2:3], 2, v[0:1]
	v_lshl_add_u64 v[0:1], v[0:1], 0, v[208:209]
	v_add_co_u32_e32 v6, vcc, s15, v0
	s_ashr_i32 s11, s10, 31
	s_nop 0
	v_addc_co_u32_e32 v7, vcc, 0, v1, vcc
	v_add_co_u32_e32 v8, vcc, s17, v0
	s_add_i32 s12, s12, s16
	s_nop 0
	v_addc_co_u32_e32 v9, vcc, 0, v1, vcc
	v_add_co_u32_e32 v34, vcc, s18, v0
	s_add_i32 s13, s13, s14
	s_nop 0
	v_addc_co_u32_e32 v35, vcc, 0, v1, vcc
	v_add_co_u32_e32 v38, vcc, s19, v0
	s_cmpk_lt_i32 s12, 0x400
	s_nop 0
	v_addc_co_u32_e32 v39, vcc, 0, v1, vcc
	v_add_co_u32_e32 v42, vcc, s20, v0
	s_nop 1
	v_addc_co_u32_e32 v43, vcc, 0, v1, vcc
	v_add_co_u32_e32 v46, vcc, s21, v0
	s_nop 1
	v_addc_co_u32_e32 v47, vcc, 0, v1, vcc
	v_add_co_u32_e32 v50, vcc, s24, v0
	s_nop 1
	v_addc_co_u32_e32 v51, vcc, 0, v1, vcc
	v_add_co_u32_e32 v54, vcc, s25, v0
	s_nop 1
	v_addc_co_u32_e32 v55, vcc, 0, v1, vcc
	v_add_co_u32_e32 v58, vcc, s26, v0
	s_nop 1
	v_addc_co_u32_e32 v59, vcc, 0, v1, vcc
	v_add_co_u32_e32 v62, vcc, s27, v0
	s_nop 1
	v_addc_co_u32_e32 v63, vcc, 0, v1, vcc
	v_add_co_u32_e32 v86, vcc, s28, v0
	s_nop 1
	v_addc_co_u32_e32 v87, vcc, 0, v1, vcc
	v_add_co_u32_e32 v90, vcc, s29, v0
	s_nop 1
	v_addc_co_u32_e32 v91, vcc, 0, v1, vcc
	v_add_co_u32_e32 v94, vcc, s30, v0
	s_nop 1
	v_addc_co_u32_e32 v95, vcc, 0, v1, vcc
	v_add_co_u32_e32 v98, vcc, s31, v0
	s_nop 1
	v_addc_co_u32_e32 v99, vcc, 0, v1, vcc
	v_add_co_u32_e32 v102, vcc, s35, v0
	s_nop 1
	v_addc_co_u32_e32 v103, vcc, 0, v1, vcc
	global_load_dwordx4 v[0:3], v[0:1], off
	s_nop 0
	global_load_dwordx4 v[26:29], v[6:7], off
	global_load_dwordx4 v[30:33], v[8:9], off
	s_nop 0
	global_load_dwordx4 v[34:37], v[34:35], off
	s_nop 0
	global_load_dwordx4 v[38:41], v[38:39], off
	s_nop 0
	global_load_dwordx4 v[42:45], v[42:43], off
	s_nop 0
	global_load_dwordx4 v[46:49], v[46:47], off
	s_nop 0
	global_load_dwordx4 v[50:53], v[50:51], off
	s_nop 0
	global_load_dwordx4 v[54:57], v[54:55], off
	s_nop 0
	global_load_dwordx4 v[58:61], v[58:59], off
	s_nop 0
	global_load_dwordx4 v[72:75], v[62:63], off
	s_nop 0
	global_load_dwordx4 v[86:89], v[86:87], off
	s_nop 0
	global_load_dwordx4 v[90:93], v[90:91], off
	s_nop 0
	global_load_dwordx4 v[94:97], v[94:95], off
	s_nop 0
	global_load_dwordx4 v[98:101], v[98:99], off
	s_nop 0
	global_load_dwordx4 v[102:105], v[102:103], off
	v_add_u32_e32 v8, s2, v65
	v_ashrrev_i32_e32 v9, 31, v8
	v_lshl_add_u64 v[6:7], s[10:11], 1, v[4:5]
	v_lshlrev_b64 v[116:117], 13, v[8:9]
	v_add_u32_e32 v62, 8, v8
	v_lshl_add_u64 v[116:117], v[6:7], 0, v[116:117]
	v_ashrrev_i32_e32 v63, 31, v62
	v_lshlrev_b64 v[62:63], 13, v[62:63]
	v_add_u32_e32 v106, 16, v8
	v_lshl_add_u64 v[62:63], v[6:7], 0, v[62:63]
	v_ashrrev_i32_e32 v107, 31, v106
	v_lshlrev_b64 v[106:107], 13, v[106:107]
	v_add_u32_e32 v108, 24, v8
	v_lshl_add_u64 v[106:107], v[6:7], 0, v[106:107]
	v_ashrrev_i32_e32 v109, 31, v108
	v_lshlrev_b64 v[108:109], 13, v[108:109]
	v_add_u32_e32 v110, 32, v8
	v_lshl_add_u64 v[108:109], v[6:7], 0, v[108:109]
	v_ashrrev_i32_e32 v111, 31, v110
	v_lshlrev_b64 v[110:111], 13, v[110:111]
	v_add_u32_e32 v112, 40, v8
	v_lshl_add_u64 v[110:111], v[6:7], 0, v[110:111]
	v_ashrrev_i32_e32 v113, 31, v112
	v_lshlrev_b64 v[112:113], 13, v[112:113]
	v_add_u32_e32 v114, 48, v8
	v_lshl_add_u64 v[112:113], v[6:7], 0, v[112:113]
	v_ashrrev_i32_e32 v115, 31, v114
	v_lshlrev_b64 v[114:115], 13, v[114:115]
	v_add_u32_e32 v8, 56, v8
	v_lshl_add_u64 v[114:115], v[6:7], 0, v[114:115]
	v_ashrrev_i32_e32 v9, 31, v8
	s_waitcnt vmcnt(0)
	ds_write_b128 v10, v[0:3]
	s_waitcnt vmcnt(14)
	ds_write_b128 v10, v[26:29] offset:1024
	s_waitcnt vmcnt(13)
	ds_write_b128 v11, v[30:33] offset:2048
	s_waitcnt vmcnt(12)
	ds_write_b128 v11, v[34:37] offset:3072
	s_waitcnt vmcnt(11)
	ds_write_b128 v12, v[38:41] offset:4096
	s_waitcnt vmcnt(10)
	ds_write_b128 v12, v[42:45] offset:5120
	s_waitcnt vmcnt(9)
	ds_write_b128 v13, v[46:49] offset:6144
	s_waitcnt vmcnt(8)
	ds_write_b128 v13, v[50:53] offset:7168
	s_waitcnt vmcnt(7)
; __device__ __forceinline__ unsigned cvt_pk_bf16(float lo, float hi) { unsigned r; asm volatile("v_cvt_pk_bf16_f32 %0, %1, %2" : "=v"(r) : "v"(lo), "v"(hi)); return r; }
; #define LAS __attribute__((address_space(3)))
; #define LDS_WAIT() asm volatile("s_waitcnt lgkmcnt(0)" ::: "memory")
; __device__ __forceinline__ void conv_item(const float* W, int ldw, int K, int c0, int k0, const float* gain, bf16_t* Wt, int n0, LAS float* scr, int lane) {
;     ...
;     for (int i = 0; i < 16; ++i) { const int k = 4 * i + kr; *(LAS f32x4*)(scr + k * 64 + (n4 ^ (((k >> 3) & 7) << 2))) = v[i]; }
;     LDS_WAIT(); asm volatile("" ::: "memory");
;     const int c = lane & 7;
; #pragma unroll
;     for (int j = 0; j < 8; ++j) { const int n = (lane >> 3) + 8 * j; const LAS float* s = scr + (8 * c) * 64 + (n ^ (c << 2));
;         u32x4 o; o.x = pg8::cvt_pk_bf16(s[0 * 64], s[1 * 64]); o.y = pg8::cvt_pk_bf16(s[2 * 64], s[3 * 64]); o.z = pg8::cvt_pk_bf16(s[4 * 64], s[5 * 64]); o.w = pg8::cvt_pk_bf16(s[6 * 64], s[7 * 64]);
;         *(u32x4*)(Wt + (size_t)(n0 + n) * K + k0 + 8 * c) = o; }
;     LDS_WAIT(); asm volatile("" ::: "memory");
	ds_write_b128 v14, v[54:57] offset:8192
	s_waitcnt vmcnt(6)
	ds_write_b128 v14, v[58:61] offset:9216
	s_waitcnt vmcnt(5)
	ds_write_b128 v15, v[72:75] offset:10240
	s_waitcnt vmcnt(4)
	ds_write_b128 v15, v[86:89] offset:11264
	s_waitcnt vmcnt(3)
	ds_write_b128 v16, v[90:93] offset:12288
	s_waitcnt vmcnt(2)
	ds_write_b128 v16, v[94:97] offset:13312
	s_waitcnt vmcnt(1)
	ds_write_b128 v17, v[98:101] offset:14336
	s_waitcnt vmcnt(0)
	ds_write_b128 v17, v[102:105] offset:15360
	s_waitcnt lgkmcnt(0)
	ds_read2st64_b32 v[0:1], v18 offset1:1
	s_waitcnt lgkmcnt(0)
	v_cvt_pk_bf16_f32 v0, v0, v1
	ds_read2st64_b32 v[2:3], v18 offset0:2 offset1:3
	s_waitcnt lgkmcnt(0)
	v_cvt_pk_bf16_f32 v1, v2, v3
	ds_read2st64_b32 v[2:3], v18 offset0:4 offset1:5
	s_waitcnt lgkmcnt(0)
	v_cvt_pk_bf16_f32 v2, v2, v3
	ds_read2st64_b32 v[26:27], v18 offset0:6 offset1:7
	s_waitcnt lgkmcnt(0)
	v_cvt_pk_bf16_f32 v3, v26, v27
	ds_read2st64_b32 v[26:27], v19 offset1:1
	global_store_dwordx4 v[116:117], v[0:3], off
	v_lshlrev_b64 v[8:9], 13, v[8:9]
	v_lshl_add_u64 v[6:7], v[6:7], 0, v[8:9]
	s_waitcnt lgkmcnt(0)
	v_cvt_pk_bf16_f32 v0, v26, v27
	ds_read2st64_b32 v[2:3], v19 offset0:2 offset1:3
	s_waitcnt lgkmcnt(0)
	v_cvt_pk_bf16_f32 v1, v2, v3
	ds_read2st64_b32 v[2:3], v19 offset0:4 offset1:5
	s_waitcnt lgkmcnt(0)
	v_cvt_pk_bf16_f32 v2, v2, v3
	ds_read2st64_b32 v[26:27], v19 offset0:6 offset1:7
	s_waitcnt lgkmcnt(0)
	v_cvt_pk_bf16_f32 v3, v26, v27
	ds_read2st64_b32 v[26:27], v20 offset1:1
	global_store_dwordx4 v[62:63], v[0:3], off
	s_waitcnt lgkmcnt(0)
	s_nop 0
	v_cvt_pk_bf16_f32 v0, v26, v27
	ds_read2st64_b32 v[2:3], v20 offset0:2 offset1:3
	s_waitcnt lgkmcnt(0)
	v_cvt_pk_bf16_f32 v1, v2, v3
	ds_read2st64_b32 v[2:3], v20 offset0:4 offset1:5
	s_waitcnt lgkmcnt(0)
	v_cvt_pk_bf16_f32 v2, v2, v3
	ds_read2st64_b32 v[26:27], v20 offset0:6 offset1:7
	s_waitcnt lgkmcnt(0)
	v_cvt_pk_bf16_f32 v3, v26, v27
	ds_read2st64_b32 v[26:27], v21 offset1:1
	global_store_dwordx4 v[106:107], v[0:3], off
	s_waitcnt lgkmcnt(0)
	s_nop 0
	v_cvt_pk_bf16_f32 v0, v26, v27
	ds_read2st64_b32 v[2:3], v21 offset0:2 offset1:3
	s_waitcnt lgkmcnt(0)
	v_cvt_pk_bf16_f32 v1, v2, v3
	ds_read2st64_b32 v[2:3], v21 offset0:4 offset1:5
	s_waitcnt lgkmcnt(0)
	v_cvt_pk_bf16_f32 v2, v2, v3
	ds_read2st64_b32 v[26:27], v21 offset0:6 offset1:7
	s_waitcnt lgkmcnt(0)
	v_cvt_pk_bf16_f32 v3, v26, v27
	ds_read2st64_b32 v[26:27], v22 offset1:1
	global_store_dwordx4 v[108:109], v[0:3], off
	s_waitcnt lgkmcnt(0)
	s_nop 0
	v_cvt_pk_bf16_f32 v0, v26, v27
	ds_read2st64_b32 v[2:3], v22 offset0:2 offset1:3
	s_waitcnt lgkmcnt(0)
	v_cvt_pk_bf16_f32 v1, v2, v3
	ds_read2st64_b32 v[2:3], v22 offset0:4 offset1:5
	s_waitcnt lgkmcnt(0)
	v_cvt_pk_bf16_f32 v2, v2, v3
	ds_read2st64_b32 v[26:27], v22 offset0:6 offset1:7
	s_waitcnt lgkmcnt(0)
	v_cvt_pk_bf16_f32 v3, v26, v27
	ds_read2st64_b32 v[26:27], v23 offset1:1
	global_store_dwordx4 v[110:111], v[0:3], off
	s_waitcnt lgkmcnt(0)
	s_nop 0
	v_cvt_pk_bf16_f32 v0, v26, v27
	ds_read2st64_b32 v[2:3], v23 offset0:2 offset1:3
	s_waitcnt lgkmcnt(0)
	v_cvt_pk_bf16_f32 v1, v2, v3
	ds_read2st64_b32 v[2:3], v23 offset0:4 offset1:5
	s_waitcnt lgkmcnt(0)
	v_cvt_pk_bf16_f32 v2, v2, v3
	ds_read2st64_b32 v[26:27], v23 offset0:6 offset1:7
	s_waitcnt lgkmcnt(0)
	v_cvt_pk_bf16_f32 v3, v26, v27
	ds_read2st64_b32 v[26:27], v24 offset1:1
	global_store_dwordx4 v[112:113], v[0:3], off
	s_waitcnt lgkmcnt(0)
	s_nop 0
	v_cvt_pk_bf16_f32 v0, v26, v27
	ds_read2st64_b32 v[2:3], v24 offset0:2 offset1:3
	s_waitcnt lgkmcnt(0)
	v_cvt_pk_bf16_f32 v1, v2, v3
	ds_read2st64_b32 v[2:3], v24 offset0:4 offset1:5
	s_waitcnt lgkmcnt(0)
	v_cvt_pk_bf16_f32 v2, v2, v3
	ds_read2st64_b32 v[26:27], v24 offset0:6 offset1:7
	s_waitcnt lgkmcnt(0)
	v_cvt_pk_bf16_f32 v3, v26, v27
	ds_read2st64_b32 v[26:27], v25 offset1:1
	global_store_dwordx4 v[114:115], v[0:3], off
	s_waitcnt lgkmcnt(0)
	s_nop 0
	v_cvt_pk_bf16_f32 v0, v26, v27
	ds_read2st64_b32 v[2:3], v25 offset0:2 offset1:3
	s_waitcnt lgkmcnt(0)
	v_cvt_pk_bf16_f32 v1, v2, v3
	ds_read2st64_b32 v[2:3], v25 offset0:4 offset1:5
	s_waitcnt lgkmcnt(0)
	v_cvt_pk_bf16_f32 v2, v2, v3
	ds_read2st64_b32 v[26:27], v25 offset0:6 offset1:7
	s_waitcnt lgkmcnt(0)
	v_cvt_pk_bf16_f32 v3, v26, v27
	global_store_dwordx4 v[6:7], v[0:3], off
	s_waitcnt lgkmcnt(0)
	s_cbranch_scc1 .LBB0_338
	s_mov_b32 s27, 0x10000
	s_mov_b32 s26, 0x8000

; #define LAS __attribute__((address_space(3)))
; __device__ __forceinline__ void conv_item(const float* W, int ldw, int K, int c0, int k0, const float* gain, bf16_t* Wt, int n0, LAS float* scr, int lane) {
;     f32x4 v[16];
;     const int kr = lane >> 4, n4 = (lane & 15) * 4;
;     const float* src = W + (size_t)(k0 + kr) * ldw + c0 + n4;
; #pragma unroll
;     for (int i = 0; i < 16; ++i) v[i] = __builtin_nontemporal_load((const f32x4*)(src + (size_t)(4 * i) * ldw));
;     if (gain) {
; #pragma unroll
;         for (int i = 0; i < 16; ++i) v[i] = v[i] * gain[k0 + 4 * i + kr];
;     }
.LBB0_346:
	s_ashr_i32 s12, s14, 31
	s_lshr_b32 s12, s12, 27
	s_add_i32 s12, s14, s12
	s_ashr_i32 s12, s12, 5
	s_lshl_b32 s13, s12, 11
	s_lshl_b32 s12, s12, 6
	v_or_b32_e32 v72, s12, v76
	v_ashrrev_i32_e32 v73, 31, v72
	s_sub_i32 s18, s15, s13
	v_lshlrev_b64 v[0:1], 13, v[72:73]
	v_lshl_add_u64 v[0:1], s[0:1], 0, v[0:1]
	s_ashr_i32 s19, s18, 31
	v_lshl_add_u64 v[0:1], s[18:19], 2, v[0:1]
	v_lshl_add_u64 v[56:57], v[0:1], 0, v[208:209]
	v_add_co_u32_e32 v4, vcc, s26, v56
	s_mov_b32 s17, 0x18000
	s_nop 0
	v_addc_co_u32_e32 v5, vcc, 0, v57, vcc
	v_add_co_u32_e32 v8, vcc, s27, v56
	global_load_dwordx4 v[0:3], v[56:57], off
	s_nop 0
	global_load_dwordx4 v[4:7], v[4:5], off
	v_addc_co_u32_e32 v9, vcc, 0, v57, vcc
	v_add_co_u32_e32 v12, vcc, s17, v56
	s_mov_b32 s17, 0x20000
	s_nop 0
	v_addc_co_u32_e32 v13, vcc, 0, v57, vcc
	v_add_co_u32_e32 v16, vcc, s17, v56
	s_mov_b32 s17, 0x28000
	s_nop 0
	v_addc_co_u32_e32 v17, vcc, 0, v57, vcc
	v_add_co_u32_e32 v20, vcc, s17, v56
	s_mov_b32 s17, 0x30000
	s_nop 0
	v_addc_co_u32_e32 v21, vcc, 0, v57, vcc
	v_add_co_u32_e32 v24, vcc, s17, v56
	s_mov_b32 s17, 0x38000
	s_nop 0
	v_addc_co_u32_e32 v25, vcc, 0, v57, vcc
	v_add_co_u32_e32 v28, vcc, s17, v56
	s_mov_b32 s17, 0x40000
	s_nop 0
	v_addc_co_u32_e32 v29, vcc, 0, v57, vcc
	v_add_co_u32_e32 v32, vcc, s17, v56
	s_mov_b32 s17, 0x48000
	s_nop 0
	v_addc_co_u32_e32 v33, vcc, 0, v57, vcc
	v_add_co_u32_e32 v36, vcc, s17, v56
	s_mov_b32 s17, 0x50000
	s_nop 0
	v_addc_co_u32_e32 v37, vcc, 0, v57, vcc
	v_add_co_u32_e32 v40, vcc, s17, v56
	s_mov_b32 s17, 0x58000
	s_nop 0
	v_addc_co_u32_e32 v41, vcc, 0, v57, vcc
	v_add_co_u32_e32 v44, vcc, s17, v56
	s_mov_b32 s17, 0x60000
	s_nop 0
	v_addc_co_u32_e32 v45, vcc, 0, v57, vcc
	v_add_co_u32_e32 v48, vcc, s17, v56
	global_load_dwordx4 v[8:11], v[8:9], off
	s_nop 0
	global_load_dwordx4 v[12:15], v[12:13], off
	v_addc_co_u32_e32 v49, vcc, 0, v57, vcc
	v_add_co_u32_e32 v52, vcc, 0x68000, v56
	global_load_dwordx4 v[16:19], v[16:17], off
	s_nop 0
	global_load_dwordx4 v[20:23], v[20:21], off
	v_addc_co_u32_e32 v53, vcc, 0, v57, vcc
	v_add_co_u32_e32 v58, vcc, 0x70000, v56
	global_load_dwordx4 v[24:27], v[24:25], off
	s_nop 0
	global_load_dwordx4 v[28:31], v[28:29], off
	v_addc_co_u32_e32 v59, vcc, 0, v57, vcc
	v_add_co_u32_e32 v60, vcc, 0x78000, v56
	global_load_dwordx4 v[32:35], v[32:33], off
	s_nop 0
	global_load_dwordx4 v[36:39], v[36:37], off
	v_addc_co_u32_e32 v61, vcc, 0, v57, vcc
	global_load_dwordx4 v[40:43], v[40:41], off
	s_nop 0
	global_load_dwordx4 v[44:47], v[44:45], off
	s_nop 0
	global_load_dwordx4 v[48:51], v[48:49], off
	s_nop 0
	global_load_dwordx4 v[52:55], v[52:53], off
	s_nop 0
	global_load_dwordx4 v[56:59], v[58:59], off
	s_nop 0
	global_load_dwordx4 v[60:63], v[60:61], off
	s_andn2_b64 vcc, exec, s[10:11]
	s_cbranch_vccnz .LBB0_345
	v_lshl_add_u64 v[72:73], v[72:73], 2, s[2:3]
	global_load_dword v92, v[72:73], off
	global_load_dword v94, v[72:73], off offset:16
	global_load_dword v96, v[72:73], off offset:32
	global_load_dword v98, v[72:73], off offset:48
	global_load_dword v100, v[72:73], off offset:64
	global_load_dword v102, v[72:73], off offset:80
	global_load_dword v104, v[72:73], off offset:96
	global_load_dword v106, v[72:73], off offset:112
	global_load_dword v108, v[72:73], off offset:128
	global_load_dword v110, v[72:73], off offset:144
	global_load_dword v112, v[72:73], off offset:160
	global_load_dword v114, v[72:73], off offset:176
	global_load_dword v116, v[72:73], off offset:192
	global_load_dword v118, v[72:73], off offset:208
	global_load_dword v120, v[72:73], off offset:224
	s_nop 0
	global_load_dword v72, v[72:73], off offset:240
	s_waitcnt vmcnt(0)
	v_pk_mul_f32 v[2:3], v[2:3], v[92:93] op_sel_hi:[1,0]
	v_pk_mul_f32 v[0:1], v[0:1], v[92:93] op_sel_hi:[1,0]
	s_waitcnt vmcnt(14)
	v_pk_mul_f32 v[6:7], v[6:7], v[94:95] op_sel_hi:[1,0]
	v_pk_mul_f32 v[4:5], v[4:5], v[94:95] op_sel_hi:[1,0]
	s_waitcnt vmcnt(13)
	v_pk_mul_f32 v[10:11], v[10:11], v[96:97] op_sel_hi:[1,0]
	v_pk_mul_f32 v[8:9], v[8:9], v[96:97] op_sel_hi:[1,0]
	s_waitcnt vmcnt(12)
	v_pk_mul_f32 v[14:15], v[14:15], v[98:99] op_sel_hi:[1,0]
	v_pk_mul_f32 v[12:13], v[12:13], v[98:99] op_sel_hi:[1,0]
	s_waitcnt vmcnt(11)
	v_pk_mul_f32 v[18:19], v[18:19], v[100:101] op_sel_hi:[1,0]
	v_pk_mul_f32 v[16:17], v[16:17], v[100:101] op_sel_hi:[1,0]
	s_waitcnt vmcnt(10)
	v_pk_mul_f32 v[22:23], v[22:23], v[102:103] op_sel_hi:[1,0]
	v_pk_mul_f32 v[20:21], v[20:21], v[102:103] op_sel_hi:[1,0]
	s_waitcnt vmcnt(9)
	v_pk_mul_f32 v[26:27], v[26:27], v[104:105] op_sel_hi:[1,0]
	v_pk_mul_f32 v[24:25], v[24:25], v[104:105] op_sel_hi:[1,0]
	s_waitcnt vmcnt(8)
	v_pk_mul_f32 v[30:31], v[30:31], v[106:107] op_sel_hi:[1,0]
	v_pk_mul_f32 v[28:29], v[28:29], v[106:107] op_sel_hi:[1,0]
	s_waitcnt vmcnt(7)
	v_pk_mul_f32 v[34:35], v[34:35], v[108:109] op_sel_hi:[1,0]
	v_pk_mul_f32 v[32:33], v[32:33], v[108:109] op_sel_hi:[1,0]
	s_waitcnt vmcnt(6)
	v_pk_mul_f32 v[38:39], v[38:39], v[110:111] op_sel_hi:[1,0]
	v_pk_mul_f32 v[36:37], v[36:37], v[110:111] op_sel_hi:[1,0]
	s_waitcnt vmcnt(5)
	v_pk_mul_f32 v[42:43], v[42:43], v[112:113] op_sel_hi:[1,0]
	v_pk_mul_f32 v[40:41], v[40:41], v[112:113] op_sel_hi:[1,0]
	s_waitcnt vmcnt(4)
	v_pk_mul_f32 v[46:47], v[46:47], v[114:115] op_sel_hi:[1,0]
	v_pk_mul_f32 v[44:45], v[44:45], v[114:115] op_sel_hi:[1,0]
	s_waitcnt vmcnt(3)
	v_pk_mul_f32 v[50:51], v[50:51], v[116:117] op_sel_hi:[1,0]
	v_pk_mul_f32 v[48:49], v[48:49], v[116:117] op_sel_hi:[1,0]
	s_waitcnt vmcnt(2)
	v_pk_mul_f32 v[54:55], v[54:55], v[118:119] op_sel_hi:[1,0]
	v_pk_mul_f32 v[52:53], v[52:53], v[118:119] op_sel_hi:[1,0]
	s_waitcnt vmcnt(1)
	v_pk_mul_f32 v[58:59], v[58:59], v[120:121] op_sel_hi:[1,0]
	v_pk_mul_f32 v[56:57], v[56:57], v[120:121] op_sel_hi:[1,0]
	s_waitcnt vmcnt(0)
	v_pk_mul_f32 v[62:63], v[62:63], v[72:73] op_sel_hi:[1,0]
	v_pk_mul_f32 v[60:61], v[60:61], v[72:73] op_sel_hi:[1,0]
	s_branch .LBB0_345
